# attention priority decay with earlier switch points (15/40/65 percent of each step)
# baseline (speedup 1.0000x reference)
.LBB0_383:
	s_setprio 3
	s_add_i32 s56, s5, s29
	s_add_i32 s3, s56, -3
	s_ashr_i32 s58, s3, 2
	s_ashr_i32 s59, s58, 31
	s_and_b32 s3, s3, 3
	s_lshl_b64 s[58:59], s[58:59], 21
	s_mul_i32 s78, s3, 0x38000
	s_add_i32 s3, s30, 0
	v_lshl_add_u64 v[80:81], v[152:153], 0, s[58:59]
	s_add_i32 s55, s3, s27
	v_lshl_add_u64 v[80:81], v[80:81], 0, s[78:79]
	s_mov_b32 m0, s55
	s_nop 0
	global_load_lds_dwordx4 v[80:81], off
	v_lshl_add_u64 v[80:81], v[156:157], 0, s[58:59]
	v_lshl_add_u64 v[80:81], v[80:81], 0, s[78:79]
	s_add_i32 m0, s55, 0x2000
	s_mov_b32 s55, s53
	global_load_lds_dwordx4 v[80:81], off
	s_mov_b32 s53, s2
	s_add_i32 s2, s55, 0
	v_add_u32_e32 v134, s2, v159
	v_exp_f32_e32 v130, v64
	v_exp_f32_e32 v131, v65
	v_exp_f32_e32 v132, v66
	v_exp_f32_e32 v133, v67
	ds_read_b128 v[64:67], v134
	ds_read_b128 v[114:117], v134 offset:512
	v_exp_f32_e32 v135, v68
	v_add_f32_e32 v68, v3, v7
	v_exp_f32_e32 v136, v69
	s_waitcnt lgkmcnt(0)
	v_mfma_f32_32x32x16_bf16 v[80:95], v[64:67], v[110:113], v[16:31]
	ds_read_b128 v[64:67], v134 offset:2048
	ds_read_b128 v[118:121], v134 offset:2560
	ds_read_b128 v[122:125], v134 offset:4096
	v_exp_f32_e32 v137, v70
	v_exp_f32_e32 v138, v71
	v_exp_f32_e32 v139, v72
	v_exp_f32_e32 v140, v73
	v_exp_f32_e32 v141, v74
	v_exp_f32_e32 v142, v75
	s_waitcnt lgkmcnt(0)
	v_mfma_f32_32x32x16_bf16 v[80:95], v[64:67], v[106:109], v[80:95]
	ds_read_b128 v[126:129], v134 offset:4608
	ds_read_b128 v[64:67], v134 offset:6144
	v_exp_f32_e32 v143, v76
	v_exp_f32_e32 v144, v77
	v_exp_f32_e32 v145, v78
	v_exp_f32_e32 v163, v79
	v_mfma_f32_32x32x16_bf16 v[80:95], v[122:125], v[102:105], v[80:95]
	ds_read_b128 v[122:125], v134 offset:6656
	s_waitcnt lgkmcnt(0)
	v_mfma_f32_32x32x16_bf16 v[80:95], v[64:67], v[98:101], v[80:95]
	v_add_f32_e32 v64, v6, v68
	v_add_f32_e32 v64, v11, v64
	s_setprio 2
	v_add_f32_e32 v64, v10, v64
	v_add_f32_e32 v64, v96, v64
	v_add_f32_e32 v64, v15, v64
	v_add_f32_e32 v64, v97, v64
	v_add_f32_e32 v134, v2, v64
	v_mfma_f32_32x32x16_bf16 v[64:79], v[114:117], v[110:113], v[16:31]
	v_add_f32_e32 v114, v5, v134
	v_add_f32_e32 v114, v4, v114
	v_add_f32_e32 v114, v9, v114
	v_add_f32_e32 v114, v8, v114
	v_add_f32_e32 v114, v12, v114
	v_add_f32_e32 v114, v13, v114
	v_add_f32_e32 v114, v14, v114
	v_mfma_f32_32x32x16_bf16 v[64:79], v[118:121], v[106:109], v[64:79]
	v_add_f32_e32 v114, v130, v114
	v_add_f32_e32 v114, v131, v114
	v_add_f32_e32 v114, v132, v114
	v_add_f32_e32 v114, v133, v114
	v_add_f32_e32 v114, v135, v114
	v_add_f32_e32 v114, v136, v114
	v_add_f32_e32 v114, v137, v114
	v_mfma_f32_32x32x16_bf16 v[64:79], v[126:129], v[102:105], v[64:79]
	v_add_f32_e32 v114, v138, v114
	v_add_f32_e32 v114, v139, v114
	v_add_f32_e32 v114, v140, v114
	v_add_f32_e32 v114, v141, v114
	v_add_f32_e32 v114, v142, v114
	v_add_f32_e32 v114, v143, v114
	v_add_f32_e32 v114, v144, v114
	v_mfma_f32_32x32x16_bf16 v[64:79], v[122:125], v[98:101], v[64:79]
	v_cvt_pk_bf16_f32 v116, v10, v96
	v_cvt_pk_bf16_f32 v10, v2, v5
	v_cvt_pk_bf16_f32 v2, v139, v140
	v_add_f32_e32 v168, v145, v114
	v_cvt_pk_bf16_f32 v114, v3, v7
	v_cvt_pk_bf16_f32 v115, v6, v11
	v_cvt_pk_bf16_f32 v117, v15, v97
	v_cvt_pk_bf16_f32 v11, v4, v9
	v_cvt_pk_bf16_f32 v12, v8, v12
	v_cvt_pk_bf16_f32 v13, v13, v14
	v_cvt_pk_bf16_f32 v6, v130, v131
	v_cvt_pk_bf16_f32 v7, v132, v133
	v_cvt_pk_bf16_f32 v8, v135, v136
	v_cvt_pk_bf16_f32 v9, v137, v138
	v_cvt_pk_bf16_f32 v3, v141, v142
	v_cvt_pk_bf16_f32 v4, v143, v144
	v_cvt_pk_bf16_f32 v5, v145, v163
	v_subrev_u32_e32 v15, 64, v162
	v_cvt_f32_i32_e32 v96, v15
	s_add_i32 s57, s53, 0
	v_add_u32_e32 v14, s57, v0
	ds_read_b64_tr_b16 v[134:135], v14 offset:8192
	ds_read_b64_tr_b16 v[136:137], v14 offset:8704
	ds_read_b64_tr_b16 v[138:139], v14 offset:9216
	ds_read_b64_tr_b16 v[140:141], v14 offset:9728
	ds_read_b64_tr_b16 v[122:123], v14 offset:12288
	ds_read_b64_tr_b16 v[124:125], v14 offset:12800
	ds_read_b64_tr_b16 v[118:119], v14 offset:13312
	ds_read_b64_tr_b16 v[120:121], v14 offset:13824
	ds_read_b64_tr_b16 v[142:143], v14 offset:10240
	ds_read_b64_tr_b16 v[144:145], v14 offset:10752
	ds_read_b64_tr_b16 v[146:147], v14 offset:11264
	ds_read_b64_tr_b16 v[148:149], v14 offset:11776
	v_add_f32_e32 v97, 1.0, v96
	ds_read_b64_tr_b16 v[130:131], v14 offset:14336
	ds_read_b64_tr_b16 v[132:133], v14 offset:14848
	ds_read_b64_tr_b16 v[126:127], v14 offset:15360
	ds_read_b64_tr_b16 v[128:129], v14 offset:15872
	v_and_b32_e32 v14, 0x7fffffff, v96
	v_and_b32_e32 v15, 0x7fffffff, v97
	v_pk_fma_f32 v[14:15], v[154:155], v[14:15], v[80:81]
	v_cmp_le_f32_e64 vcc, |v97|, s77
	v_pk_add_f32 v[164:165], v[96:97], s[26:27] op_sel_hi:[1,0]
	s_waitcnt lgkmcnt(14)
	v_mfma_f32_32x32x16_bf16 v[32:47], v[134:137], v[114:117], v[32:47]
	v_cndmask_b32_e32 v80, v197, v15, vcc
	v_cmp_le_f32_e64 vcc, |v96|, s77
	v_and_b32_e32 v15, 0x7fffffff, v165
	v_add_f32_e64 v134, v96, s18
	v_add_f32_e64 v135, v96, s19
	v_cndmask_b32_e32 v81, v197, v14, vcc
	v_and_b32_e32 v14, 0x7fffffff, v164
	v_pk_fma_f32 v[64:65], v[154:155], v[14:15], v[64:65]
	v_cmp_le_f32_e64 vcc, |v165|, s77
	s_waitcnt lgkmcnt(10)
	v_mfma_f32_32x32x16_bf16 v[48:63], v[122:125], v[114:117], v[48:63]
	v_add_f32_e64 v136, v134, s26
	v_add_f32_e64 v137, v135, s26
	v_cndmask_b32_e32 v14, v197, v65, vcc
	v_cmp_le_f32_e64 vcc, |v164|, s77
	v_add_f32_e64 v164, v96, s8
	v_add_f32_e64 v165, v96, s9
	v_pk_add_f32 v[166:167], v[164:165], s[26:27] op_sel_hi:[1,0]
	v_cndmask_b32_e32 v15, v197, v64, vcc
	v_and_b32_e32 v65, 0x7fffffff, v167
	v_and_b32_e32 v64, 0x7fffffff, v166
	v_pk_fma_f32 v[66:67], v[154:155], v[64:65], v[66:67]
	v_cmp_le_f32_e64 vcc, |v167|, s77
	v_mfma_f32_32x32x16_bf16 v[32:47], v[138:141], v[10:13], v[32:47]
	s_setprio 1
	s_nop 0
	v_cndmask_b32_e32 v64, v197, v67, vcc
	v_cmp_le_f32_e64 vcc, |v166|, s77
	v_and_b32_e32 v67, 0x7fffffff, v165
	s_nop 0
	v_cndmask_b32_e32 v65, v197, v66, vcc
	v_and_b32_e32 v66, 0x7fffffff, v164
	v_pk_fma_f32 v[82:83], v[154:155], v[66:67], v[82:83]
	v_cmp_le_f32_e64 vcc, |v165|, s77
	s_waitcnt lgkmcnt(8)
	v_mfma_f32_32x32x16_bf16 v[48:63], v[118:121], v[10:13], v[48:63]
	v_cndmask_b32_e32 v66, v197, v83, vcc
	v_cmp_le_f32_e64 vcc, |v164|, s77
	v_add_f32_e64 v164, v96, s10
	v_add_f32_e64 v165, v96, s11
	v_add_f32_e64 v166, v164, s26
	v_add_f32_e64 v167, v165, s26
	v_cndmask_b32_e32 v67, v197, v82, vcc
	v_and_b32_e32 v83, 0x7fffffff, v167
	v_and_b32_e32 v82, 0x7fffffff, v166
	v_pk_fma_f32 v[68:69], v[154:155], v[82:83], v[68:69]
	v_cmp_le_f32_e64 vcc, |v167|, s77
	s_waitcnt lgkmcnt(6)
	v_mfma_f32_32x32x16_bf16 v[32:47], v[142:145], v[6:9], v[32:47]
	v_cndmask_b32_e32 v82, v197, v69, vcc
	v_cmp_le_f32_e64 vcc, |v166|, s77
	v_and_b32_e32 v69, 0x7fffffff, v165
	s_nop 0
	v_cndmask_b32_e32 v83, v197, v68, vcc
	v_and_b32_e32 v68, 0x7fffffff, v164
	v_pk_fma_f32 v[84:85], v[154:155], v[68:69], v[84:85]
	v_cmp_le_f32_e64 vcc, |v165|, s77
	s_waitcnt lgkmcnt(2)
	v_mfma_f32_32x32x16_bf16 v[48:63], v[130:133], v[6:9], v[48:63]
	v_cndmask_b32_e32 v68, v197, v85, vcc
	v_cmp_le_f32_e64 vcc, |v164|, s77
	v_add_f32_e64 v164, v96, s12
	v_add_f32_e64 v165, v96, s13
	v_add_f32_e64 v166, v164, s26
	v_add_f32_e64 v167, v165, s26
	v_cndmask_b32_e32 v69, v197, v84, vcc
	v_and_b32_e32 v85, 0x7fffffff, v167
	v_and_b32_e32 v84, 0x7fffffff, v166
	v_pk_fma_f32 v[70:71], v[154:155], v[84:85], v[70:71]
	v_cmp_le_f32_e64 vcc, |v167|, s77
	v_mfma_f32_32x32x16_bf16 v[32:47], v[146:149], v[2:5], v[32:47]
	s_nop 0
	v_cndmask_b32_e32 v84, v197, v71, vcc
	v_cmp_le_f32_e64 vcc, |v166|, s77
	v_and_b32_e32 v71, 0x7fffffff, v165
	s_nop 0
	v_cndmask_b32_e32 v85, v197, v70, vcc
	v_and_b32_e32 v70, 0x7fffffff, v164
	v_pk_fma_f32 v[86:87], v[154:155], v[70:71], v[86:87]
	v_cmp_le_f32_e64 vcc, |v165|, s77
	s_waitcnt lgkmcnt(0)
	v_mfma_f32_32x32x16_bf16 v[48:63], v[126:129], v[2:5], v[48:63]
	v_cndmask_b32_e32 v70, v197, v87, vcc
	v_cmp_le_f32_e64 vcc, |v164|, s77
	v_add_f32_e64 v164, v96, s14
	v_add_f32_e64 v165, v96, s15
	v_add_f32_e64 v166, v164, s26
	v_add_f32_e64 v167, v165, s26
	v_cndmask_b32_e32 v71, v197, v86, vcc
	v_and_b32_e32 v87, 0x7fffffff, v167
	v_and_b32_e32 v86, 0x7fffffff, v166
	v_pk_fma_f32 v[72:73], v[154:155], v[86:87], v[72:73]
	v_cmp_le_f32_e64 vcc, |v167|, s77
	s_nop 1
	v_cndmask_b32_e32 v86, v197, v73, vcc
	v_cmp_le_f32_e64 vcc, |v166|, s77
	v_and_b32_e32 v73, 0x7fffffff, v165
	s_nop 0
	v_cndmask_b32_e32 v87, v197, v72, vcc
	v_and_b32_e32 v72, 0x7fffffff, v164
	v_pk_fma_f32 v[88:89], v[154:155], v[72:73], v[88:89]
	v_cmp_le_f32_e64 vcc, |v165|, s77
	s_nop 1
	v_cndmask_b32_e32 v72, v197, v89, vcc
	v_cmp_le_f32_e64 vcc, |v164|, s77
	v_pk_add_f32 v[164:165], v[96:97], s[16:17] op_sel_hi:[0,1]
	v_pk_add_f32 v[166:167], v[164:165], s[26:27] op_sel_hi:[1,0]
	v_cndmask_b32_e32 v73, v197, v88, vcc
	v_and_b32_e32 v89, 0x7fffffff, v167
	v_and_b32_e32 v88, 0x7fffffff, v166
	v_pk_fma_f32 v[74:75], v[154:155], v[88:89], v[74:75]
	v_cmp_le_f32_e64 vcc, |v167|, s77
	v_pk_add_f32 v[96:97], v[96:97], s[20:21] op_sel_hi:[0,1]
	s_nop 0
	v_cndmask_b32_e32 v88, v197, v75, vcc
	v_cmp_le_f32_e64 vcc, |v166|, s77
	v_and_b32_e32 v75, 0x7fffffff, v165
	s_nop 0
	v_cndmask_b32_e32 v89, v197, v74, vcc
	v_and_b32_e32 v74, 0x7fffffff, v164
	v_pk_fma_f32 v[90:91], v[154:155], v[74:75], v[90:91]
	v_cmp_le_f32_e64 vcc, |v165|, s77
	s_nop 1
	v_cndmask_b32_e32 v74, v197, v91, vcc
	v_cmp_le_f32_e64 vcc, |v164|, s77
	s_setprio 0
	v_and_b32_e32 v91, 0x7fffffff, v137
	s_nop 0
	v_cndmask_b32_e32 v75, v197, v90, vcc
	v_and_b32_e32 v90, 0x7fffffff, v136
	v_pk_fma_f32 v[76:77], v[154:155], v[90:91], v[76:77]
	v_cmp_le_f32_e64 vcc, |v137|, s77
	s_nop 1
	v_cndmask_b32_e32 v90, v197, v77, vcc
	v_cmp_le_f32_e64 vcc, |v136|, s77
	v_and_b32_e32 v77, 0x7fffffff, v135
	s_nop 0
	v_cndmask_b32_e32 v91, v197, v76, vcc
	v_and_b32_e32 v76, 0x7fffffff, v134
	v_pk_fma_f32 v[92:93], v[154:155], v[76:77], v[92:93]
	v_cmp_le_f32_e64 vcc, |v135|, s77
	s_nop 1
	v_cndmask_b32_e32 v76, v197, v93, vcc
	v_cmp_le_f32_e64 vcc, |v134|, s77
	v_pk_add_f32 v[134:135], v[96:97], s[26:27] op_sel_hi:[1,0]
	s_nop 0
	v_cndmask_b32_e32 v77, v197, v92, vcc
	v_and_b32_e32 v93, 0x7fffffff, v135
	v_and_b32_e32 v92, 0x7fffffff, v134
	v_pk_fma_f32 v[78:79], v[154:155], v[92:93], v[78:79]
	v_cmp_le_f32_e64 vcc, |v135|, s77
	s_nop 1
	v_cndmask_b32_e32 v92, v197, v79, vcc
	v_cmp_le_f32_e64 vcc, |v134|, s77
	v_and_b32_e32 v79, 0x7fffffff, v97
	s_nop 0
	v_cndmask_b32_e32 v93, v197, v78, vcc
	v_and_b32_e32 v78, 0x7fffffff, v96
	v_pk_fma_f32 v[94:95], v[154:155], v[78:79], v[94:95]
	v_cmp_le_f32_e64 vcc, |v97|, s77
	s_nop 1
	v_cndmask_b32_e32 v78, v197, v95, vcc
	v_max_f32_e32 v95, v80, v14
	v_cmp_le_f32_e64 vcc, |v96|, s77
	v_max3_f32 v96, v81, v15, v67
	v_max3_f32 v10, v95, v66, v64
	v_max3_f32 v11, v96, v65, v69
	v_max3_f32 v10, v10, v68, v82
	v_max3_f32 v11, v11, v83, v71
	v_max3_f32 v10, v10, v70, v84
	v_max3_f32 v11, v11, v85, v73
	v_max3_f32 v10, v10, v72, v86
	v_max3_f32 v6, v11, v87, v75
	v_max3_f32 v7, v10, v74, v88
	v_cndmask_b32_e32 v79, v197, v94, vcc
	v_max3_f32 v6, v6, v89, v77
	v_max3_f32 v7, v7, v76, v90
	v_max3_f32 v6, v6, v91, v79
	v_max3_f32 v7, v7, v78, v92
	v_add_f32_e32 v94, v163, v168
	v_max3_f32 v2, v6, v93, v7
	v_add_f32_e32 v161, v161, v94
	v_cmp_lt_f32_e32 vcc, s33, v2
	s_cbranch_vccz .LBB0_385
	v_mov_b32_e32 v3, v2
	s_nop 1
	v_permlane32_swap_b32 v2, v3
	s_nop 1
	s_nop 0
	v_max3_f32 v3, v2, v3, 0
	v_exp_f32_e64 v2, -v3
	v_add_f32_e32 v151, v151, v3
	v_xor_b32_e32 v16, 0x80000000, v151
	v_sub_f32_e32 v81, v81, v3
	v_sub_f32_e32 v80, v80, v3
	v_sub_f32_e32 v67, v67, v3
	v_sub_f32_e32 v66, v66, v3
	v_sub_f32_e32 v69, v69, v3
	v_sub_f32_e32 v68, v68, v3
	v_sub_f32_e32 v71, v71, v3
	v_sub_f32_e32 v70, v70, v3
	v_sub_f32_e32 v73, v73, v3
	v_sub_f32_e32 v72, v72, v3
	v_sub_f32_e32 v75, v75, v3
	v_sub_f32_e32 v74, v74, v3
	v_sub_f32_e32 v77, v77, v3
	v_sub_f32_e32 v76, v76, v3
	v_sub_f32_e32 v79, v79, v3
	v_sub_f32_e32 v78, v78, v3
	v_sub_f32_e32 v15, v15, v3
	v_sub_f32_e32 v14, v14, v3
	v_sub_f32_e32 v65, v65, v3
	v_sub_f32_e32 v64, v64, v3
	v_sub_f32_e32 v83, v83, v3
	v_sub_f32_e32 v82, v82, v3
	v_sub_f32_e32 v85, v85, v3
	v_sub_f32_e32 v84, v84, v3
	v_sub_f32_e32 v87, v87, v3
	v_sub_f32_e32 v86, v86, v3
	v_sub_f32_e32 v89, v89, v3
	v_sub_f32_e32 v88, v88, v3
	v_sub_f32_e32 v91, v91, v3
	v_sub_f32_e32 v90, v90, v3
	v_sub_f32_e32 v93, v93, v3
	v_sub_f32_e32 v92, v92, v3
	v_mov_b32_e32 v17, v16
	v_mov_b32_e32 v18, v16
	v_mov_b32_e32 v19, v16
	v_mov_b32_e32 v20, v16
	v_mov_b32_e32 v21, v16
	v_mov_b32_e32 v22, v16
	v_mov_b32_e32 v23, v16
	v_mov_b32_e32 v24, v16
	v_mov_b32_e32 v25, v16
	v_mov_b32_e32 v26, v16
	v_mov_b32_e32 v27, v16
	v_mov_b32_e32 v28, v16
	v_mov_b32_e32 v29, v16
	v_mov_b32_e32 v30, v16
	v_mov_b32_e32 v31, v16
	v_pk_mul_f32 v[46:47], v[46:47], v[2:3] op_sel_hi:[1,0]
	v_pk_mul_f32 v[44:45], v[44:45], v[2:3] op_sel_hi:[1,0]
	v_pk_mul_f32 v[42:43], v[42:43], v[2:3] op_sel_hi:[1,0]
	v_pk_mul_f32 v[40:41], v[40:41], v[2:3] op_sel_hi:[1,0]
	v_pk_mul_f32 v[38:39], v[38:39], v[2:3] op_sel_hi:[1,0]
	v_pk_mul_f32 v[36:37], v[36:37], v[2:3] op_sel_hi:[1,0]
	v_pk_mul_f32 v[34:35], v[34:35], v[2:3] op_sel_hi:[1,0]
	v_pk_mul_f32 v[32:33], v[32:33], v[2:3] op_sel_hi:[1,0]
	v_pk_mul_f32 v[62:63], v[62:63], v[2:3] op_sel_hi:[1,0]
	v_pk_mul_f32 v[60:61], v[60:61], v[2:3] op_sel_hi:[1,0]
	v_pk_mul_f32 v[58:59], v[58:59], v[2:3] op_sel_hi:[1,0]
	v_pk_mul_f32 v[56:57], v[56:57], v[2:3] op_sel_hi:[1,0]
	v_pk_mul_f32 v[54:55], v[54:55], v[2:3] op_sel_hi:[1,0]
	v_pk_mul_f32 v[52:53], v[52:53], v[2:3] op_sel_hi:[1,0]
	v_pk_mul_f32 v[50:51], v[50:51], v[2:3] op_sel_hi:[1,0]
	v_pk_mul_f32 v[48:49], v[48:49], v[2:3] op_sel_hi:[1,0]
	v_mul_f32_e32 v161, v161, v2

.LBB0_387:
	v_exp_f32_e32 v122, v81
	v_exp_f32_e32 v123, v80
	v_exp_f32_e32 v124, v67
	v_exp_f32_e32 v125, v66
	v_exp_f32_e32 v126, v69
	v_exp_f32_e32 v127, v68
	v_exp_f32_e32 v128, v71
	v_exp_f32_e32 v129, v70
	v_exp_f32_e32 v130, v73
	v_exp_f32_e32 v131, v72
	v_exp_f32_e32 v132, v75
	v_exp_f32_e32 v133, v74
	v_exp_f32_e32 v134, v77
	v_exp_f32_e32 v135, v76
	v_exp_f32_e32 v136, v79
	v_exp_f32_e32 v137, v78
	v_add_u32_e32 v94, s3, v159
	ds_read_b128 v[2:5], v94
	ds_read_b128 v[6:9], v94 offset:512
	v_exp_f32_e32 v138, v87
	v_exp_f32_e32 v139, v86
	v_exp_f32_e32 v140, v89
	s_waitcnt lgkmcnt(0)
	v_mfma_f32_32x32x16_bf16 v[66:81], v[2:5], v[110:113], v[16:31]
	ds_read_b128 v[2:5], v94 offset:2048
	ds_read_b128 v[10:13], v94 offset:2560
	v_exp_f32_e32 v141, v88
	v_exp_f32_e32 v142, v91
	v_exp_f32_e32 v143, v90
	v_exp_f32_e32 v144, v93
	v_exp_f32_e32 v165, v92
	s_waitcnt lgkmcnt(0)
	v_mfma_f32_32x32x16_bf16 v[66:81], v[2:5], v[106:109], v[66:81]
	ds_read_b128 v[2:5], v94 offset:4096
	ds_read_b128 v[114:117], v94 offset:4608
	s_waitcnt lgkmcnt(0)
	v_mfma_f32_32x32x16_bf16 v[66:81], v[2:5], v[102:105], v[66:81]
	ds_read_b128 v[2:5], v94 offset:6144
	ds_read_b128 v[118:121], v94 offset:6656
	s_waitcnt lgkmcnt(0)
	v_mfma_f32_32x32x16_bf16 v[66:81], v[2:5], v[98:101], v[66:81]
	v_exp_f32_e32 v2, v15
	s_setprio 2
	v_exp_f32_e32 v3, v14
	v_exp_f32_e32 v4, v65
	v_exp_f32_e32 v5, v64
	v_exp_f32_e32 v14, v83
	v_exp_f32_e32 v15, v82
	v_exp_f32_e32 v64, v85
	v_exp_f32_e32 v65, v84
	v_mfma_f32_32x32x16_bf16 v[82:97], v[6:9], v[110:113], v[16:31]
	v_add_f32_e32 v6, v122, v123
	v_add_f32_e32 v6, v124, v6
	v_add_f32_e32 v6, v125, v6
	v_add_f32_e32 v6, v126, v6
	v_add_f32_e32 v6, v127, v6
	v_add_f32_e32 v6, v128, v6
	v_add_f32_e32 v6, v129, v6
	v_mfma_f32_32x32x16_bf16 v[82:97], v[10:13], v[106:109], v[82:97]
	v_add_f32_e32 v6, v130, v6
	v_add_f32_e32 v6, v131, v6
	v_add_f32_e32 v6, v132, v6
	v_add_f32_e32 v6, v133, v6
	v_add_f32_e32 v6, v134, v6
	v_add_f32_e32 v6, v135, v6
	v_add_f32_e32 v6, v136, v6
	v_mfma_f32_32x32x16_bf16 v[82:97], v[114:117], v[102:105], v[82:97]
	v_add_f32_e32 v6, v137, v6
	v_add_f32_e32 v6, v2, v6
	v_add_f32_e32 v6, v3, v6
	v_add_f32_e32 v6, v4, v6
	v_add_f32_e32 v6, v5, v6
	v_add_f32_e32 v6, v14, v6
	v_add_f32_e32 v6, v15, v6
	v_add_f32_e32 v6, v64, v6
	v_add_f32_e32 v6, v65, v6
	v_mfma_f32_32x32x16_bf16 v[82:97], v[118:121], v[98:101], v[82:97]
	v_add_f32_e32 v6, v138, v6
	v_add_f32_e32 v6, v139, v6
	v_add_f32_e32 v6, v140, v6
	v_add_f32_e32 v6, v141, v6
	v_add_f32_e32 v6, v142, v6
	v_add_f32_e32 v6, v143, v6
	v_add_f32_e32 v168, v144, v6
	v_cvt_pk_bf16_f32 v6, v2, v3
	v_cvt_pk_bf16_f32 v2, v138, v139
	v_cvt_pk_bf16_f32 v122, v122, v123
	v_cvt_pk_bf16_f32 v123, v124, v125
	v_cvt_pk_bf16_f32 v124, v126, v127
	v_cvt_pk_bf16_f32 v125, v128, v129
	v_cvt_pk_bf16_f32 v114, v130, v131
	v_cvt_pk_bf16_f32 v115, v132, v133
	v_cvt_pk_bf16_f32 v116, v134, v135
	v_cvt_pk_bf16_f32 v117, v136, v137
	v_cvt_pk_bf16_f32 v7, v4, v5
	v_cvt_pk_bf16_f32 v8, v14, v15
	v_cvt_pk_bf16_f32 v9, v64, v65
	v_cvt_pk_bf16_f32 v3, v140, v141
	v_cvt_pk_bf16_f32 v4, v142, v143
	v_cvt_pk_bf16_f32 v5, v144, v165
	v_cvt_f32_i32_e32 v14, v162
	v_add_u32_e32 v12, s2, v0
	ds_read_b64_tr_b16 v[146:147], v12 offset:8192
	ds_read_b64_tr_b16 v[148:149], v12 offset:8704
	ds_read_b64_tr_b16 v[130:131], v12 offset:12288
	ds_read_b64_tr_b16 v[132:133], v12 offset:12800
	ds_read_b64_tr_b16 v[138:139], v12 offset:9216
	ds_read_b64_tr_b16 v[140:141], v12 offset:9728
	ds_read_b64_tr_b16 v[126:127], v12 offset:13312
	ds_read_b64_tr_b16 v[128:129], v12 offset:13824
	ds_read_b64_tr_b16 v[134:135], v12 offset:10240
	ds_read_b64_tr_b16 v[136:137], v12 offset:10752
	ds_read_b64_tr_b16 v[118:119], v12 offset:14336
	ds_read_b64_tr_b16 v[120:121], v12 offset:14848
	ds_read_b64_tr_b16 v[142:143], v12 offset:11264
	ds_read_b64_tr_b16 v[144:145], v12 offset:11776
	ds_read_b64_tr_b16 v[10:11], v12 offset:15360
	ds_read_b64_tr_b16 v[12:13], v12 offset:15872
	s_waitcnt lgkmcnt(14)
	v_mfma_f32_32x32x16_bf16 v[32:47], v[146:149], v[122:125], v[32:47]
	v_add_f32_e32 v15, 1.0, v14
	v_and_b32_e32 v64, 0x7fffffff, v14
	v_and_b32_e32 v65, 0x7fffffff, v15
	v_fma_f32 v64, v154, v64, v66
	v_fma_f32 v65, v155, v65, v67
	v_cmp_le_f32_e64 vcc, |v14|, s77
	v_cmp_le_f32_e64 s[2:3], |v15|, s77
	s_mov_b32 s78, s76
	v_cndmask_b32_e32 v164, v197, v64, vcc
	v_cndmask_b32_e64 v163, v197, v65, s[2:3]
	v_pk_add_f32 v[64:65], v[14:15], s[26:27] op_sel_hi:[1,0]
	s_waitcnt lgkmcnt(12)
	v_mfma_f32_32x32x16_bf16 v[48:63], v[130:133], v[122:125], v[48:63]
	v_and_b32_e32 v67, 0x7fffffff, v65
	v_and_b32_e32 v66, 0x7fffffff, v64
	v_fma_f32 v66, v154, v66, v82
	v_fma_f32 v67, v155, v67, v83
	v_cmp_le_f32_e64 vcc, |v64|, s77
	v_cmp_le_f32_e64 s[2:3], |v65|, s77
	v_pk_add_f32 v[82:83], v[14:15], s[8:9] op_sel_hi:[0,1]
	v_cndmask_b32_e32 v64, v197, v66, vcc
	v_cndmask_b32_e64 v65, v197, v67, s[2:3]
	v_pk_add_f32 v[66:67], v[82:83], s[26:27] op_sel_hi:[1,0]
	s_waitcnt lgkmcnt(10)
	v_mfma_f32_32x32x16_bf16 v[32:47], v[138:141], v[114:117], v[32:47]
	v_and_b32_e32 v167, 0x7fffffff, v67
	v_and_b32_e32 v166, 0x7fffffff, v66
	s_setprio 1
	v_fma_f32 v84, v154, v166, v84
	v_fma_f32 v85, v155, v167, v85
	v_cmp_le_f32_e64 vcc, |v66|, s77
	v_cmp_le_f32_e64 s[2:3], |v67|, s77
	s_nop 0
	v_cndmask_b32_e32 v66, v197, v84, vcc
	v_cndmask_b32_e64 v67, v197, v85, s[2:3]
	v_and_b32_e32 v85, 0x7fffffff, v83
	v_and_b32_e32 v84, 0x7fffffff, v82
	v_pk_fma_f32 v[68:69], v[154:155], v[84:85], v[68:69]
	v_cmp_le_f32_e64 s[2:3], |v83|, s77
	v_cmp_le_f32_e64 vcc, |v82|, s77
	s_waitcnt lgkmcnt(8)
	v_mfma_f32_32x32x16_bf16 v[48:63], v[126:129], v[114:117], v[48:63]
	v_cndmask_b32_e64 v15, v197, v69, s[2:3]
	v_add_f32_e64 v84, v14, s10
	v_add_f32_e64 v85, v14, s11
	v_cndmask_b32_e32 v82, v197, v68, vcc
	v_add_f32_e64 v68, v84, s26
	v_add_f32_e64 v69, v85, s26
	v_and_b32_e32 v167, 0x7fffffff, v69
	v_and_b32_e32 v166, 0x7fffffff, v68
	v_pk_fma_f32 v[86:87], v[154:155], v[166:167], v[86:87]
	v_cmp_le_f32_e64 vcc, |v68|, s77
	v_cmp_le_f32_e64 s[2:3], |v69|, s77
	s_waitcnt lgkmcnt(6)
	v_mfma_f32_32x32x16_bf16 v[32:47], v[134:137], v[6:9], v[32:47]
	v_cndmask_b32_e32 v68, v197, v86, vcc
	v_cndmask_b32_e64 v69, v197, v87, s[2:3]
	v_and_b32_e32 v87, 0x7fffffff, v85
	v_and_b32_e32 v86, 0x7fffffff, v84
	v_fma_f32 v70, v154, v86, v70
	v_fma_f32 v71, v155, v87, v71
	v_cmp_le_f32_e64 vcc, |v84|, s77
	v_cmp_le_f32_e64 s[2:3], |v85|, s77
	v_pk_add_f32 v[86:87], v[14:15], s[12:13] op_sel_hi:[0,1]
	v_cndmask_b32_e32 v84, v197, v70, vcc
	v_cndmask_b32_e64 v83, v197, v71, s[2:3]
	v_pk_add_f32 v[70:71], v[86:87], s[26:27] op_sel_hi:[1,0]
	s_waitcnt lgkmcnt(4)
	v_mfma_f32_32x32x16_bf16 v[48:63], v[118:121], v[6:9], v[48:63]
	v_and_b32_e32 v167, 0x7fffffff, v71
	v_and_b32_e32 v166, 0x7fffffff, v70
	v_fma_f32 v88, v154, v166, v88
	v_fma_f32 v89, v155, v167, v89
	v_cmp_le_f32_e64 vcc, |v70|, s77
	v_cmp_le_f32_e64 s[2:3], |v71|, s77
	s_nop 0
	v_cndmask_b32_e32 v70, v197, v88, vcc
	v_cndmask_b32_e64 v71, v197, v89, s[2:3]
	v_and_b32_e32 v89, 0x7fffffff, v87
	v_and_b32_e32 v88, 0x7fffffff, v86
	v_pk_fma_f32 v[72:73], v[154:155], v[88:89], v[72:73]
	v_cmp_le_f32_e64 vcc, |v86|, s77
	v_cmp_le_f32_e64 s[2:3], |v87|, s77
	v_pk_add_f32 v[88:89], v[14:15], s[14:15] op_sel_hi:[0,1]
	v_cndmask_b32_e32 v86, v197, v72, vcc
	v_cndmask_b32_e64 v85, v197, v73, s[2:3]
	v_pk_add_f32 v[72:73], v[88:89], s[26:27] op_sel_hi:[1,0]
	s_waitcnt lgkmcnt(2)
	v_mfma_f32_32x32x16_bf16 v[32:47], v[142:145], v[2:5], v[32:47]
	v_and_b32_e32 v167, 0x7fffffff, v73
	v_and_b32_e32 v166, 0x7fffffff, v72
	v_fma_f32 v90, v154, v166, v90
	v_fma_f32 v91, v155, v167, v91
	v_cmp_le_f32_e64 vcc, |v72|, s77
	v_cmp_le_f32_e64 s[2:3], |v73|, s77
	s_nop 0
	v_cndmask_b32_e32 v72, v197, v90, vcc
	v_cndmask_b32_e64 v73, v197, v91, s[2:3]
	v_and_b32_e32 v91, 0x7fffffff, v89
	v_and_b32_e32 v90, 0x7fffffff, v88
	v_pk_fma_f32 v[74:75], v[154:155], v[90:91], v[74:75]
	v_cmp_le_f32_e64 vcc, |v88|, s77
	v_cmp_le_f32_e64 s[2:3], |v89|, s77
	v_pk_add_f32 v[90:91], v[14:15], s[16:17] op_sel_hi:[0,1]
	v_cndmask_b32_e32 v88, v197, v74, vcc
	v_cndmask_b32_e64 v87, v197, v75, s[2:3]
	v_pk_add_f32 v[74:75], v[90:91], s[26:27] op_sel_hi:[1,0]
	s_waitcnt lgkmcnt(0)
	v_mfma_f32_32x32x16_bf16 v[48:63], v[10:13], v[2:5], v[48:63]
	v_and_b32_e32 v167, 0x7fffffff, v75
	v_and_b32_e32 v166, 0x7fffffff, v74
	v_fma_f32 v92, v154, v166, v92
	v_fma_f32 v93, v155, v167, v93
	v_cmp_le_f32_e64 vcc, |v74|, s77
	v_cmp_le_f32_e64 s[2:3], |v75|, s77
	s_nop 0
	v_cndmask_b32_e32 v74, v197, v92, vcc
	v_cndmask_b32_e64 v75, v197, v93, s[2:3]
	v_and_b32_e32 v93, 0x7fffffff, v91
	v_and_b32_e32 v92, 0x7fffffff, v90
	v_pk_fma_f32 v[76:77], v[154:155], v[92:93], v[76:77]
	v_cmp_le_f32_e64 vcc, |v90|, s77
	v_cmp_le_f32_e64 s[2:3], |v91|, s77
	v_pk_add_f32 v[92:93], v[14:15], s[18:19] op_sel_hi:[0,1]
	v_cndmask_b32_e32 v90, v197, v76, vcc
	v_cndmask_b32_e64 v89, v197, v77, s[2:3]
	v_pk_add_f32 v[76:77], v[92:93], s[26:27] op_sel_hi:[1,0]
	s_nop 0
	v_and_b32_e32 v167, 0x7fffffff, v77
	v_and_b32_e32 v166, 0x7fffffff, v76
	v_pk_fma_f32 v[94:95], v[154:155], v[166:167], v[94:95]
	v_cmp_le_f32_e64 vcc, |v76|, s77
	v_cmp_le_f32_e64 s[2:3], |v77|, s77
	s_setprio 0
	s_nop 0
	v_cndmask_b32_e32 v76, v197, v94, vcc
	v_cndmask_b32_e64 v77, v197, v95, s[2:3]
	v_and_b32_e32 v95, 0x7fffffff, v93
	v_and_b32_e32 v94, 0x7fffffff, v92
	v_pk_fma_f32 v[78:79], v[154:155], v[94:95], v[78:79]
	v_cmp_le_f32_e64 vcc, |v92|, s77
	v_cmp_le_f32_e64 s[2:3], |v93|, s77
	v_pk_add_f32 v[94:95], v[14:15], s[20:21] op_sel_hi:[0,1]
	v_cndmask_b32_e32 v92, v197, v78, vcc
	v_cndmask_b32_e64 v91, v197, v79, s[2:3]
	v_pk_add_f32 v[78:79], v[94:95], s[26:27] op_sel_hi:[1,0]
	v_max_f32_e32 v93, v163, v65
	v_and_b32_e32 v167, 0x7fffffff, v79
	v_and_b32_e32 v166, 0x7fffffff, v78
	v_pk_fma_f32 v[96:97], v[154:155], v[166:167], v[96:97]
	v_cmp_le_f32_e64 vcc, |v78|, s77
	v_max3_f32 v93, v93, v15, v67
	v_max3_f32 v93, v93, v83, v69
	v_cndmask_b32_e32 v78, v197, v96, vcc
	v_and_b32_e32 v96, 0x7fffffff, v94
	v_cmp_le_f32_e64 vcc, |v94|, s77
	v_max3_f32 v94, v164, v64, v82
	v_max3_f32 v94, v94, v66, v84
	v_cmp_le_f32_e64 s[2:3], |v79|, s77
	v_max3_f32 v94, v94, v68, v86
	v_max3_f32 v93, v93, v85, v71
	v_cndmask_b32_e64 v79, v197, v97, s[2:3]
	v_and_b32_e32 v97, 0x7fffffff, v95
	v_max3_f32 v94, v94, v70, v88
	v_max3_f32 v93, v93, v87, v73
	v_pk_fma_f32 v[80:81], v[154:155], v[96:97], v[80:81]
	v_cmp_le_f32_e64 s[2:3], |v95|, s77
	v_max3_f32 v94, v94, v72, v90
	v_max3_f32 v93, v93, v89, v75
	v_cndmask_b32_e64 v14, v197, v81, s[2:3]
	v_cndmask_b32_e32 v80, v197, v80, vcc
	v_max3_f32 v94, v94, v74, v92
	v_max3_f32 v93, v93, v91, v77
	v_max3_f32 v94, v94, v76, v80
	v_max3_f32 v93, v93, v14, v79
	v_add_f32_e32 v81, v165, v168
	v_max3_f32 v2, v94, v78, v93
	v_add_f32_e32 v161, v161, v81
	v_cmp_lt_f32_e32 vcc, s33, v2
	s_cbranch_vccz .LBB0_389
	v_mov_b32_e32 v3, v2
	s_nop 1
	v_permlane32_swap_b32 v2, v3
	s_nop 1
	s_nop 0
	v_max3_f32 v3, v2, v3, 0
	v_exp_f32_e64 v2, -v3
	v_add_f32_e32 v151, v151, v3
	v_xor_b32_e32 v16, 0x80000000, v151
	v_sub_f32_e32 v164, v164, v3
	v_pk_mul_f32 v[46:47], v[46:47], v[2:3] op_sel_hi:[1,0]
	v_pk_mul_f32 v[44:45], v[44:45], v[2:3] op_sel_hi:[1,0]
	v_pk_mul_f32 v[42:43], v[42:43], v[2:3] op_sel_hi:[1,0]
	v_pk_mul_f32 v[40:41], v[40:41], v[2:3] op_sel_hi:[1,0]
	v_pk_mul_f32 v[38:39], v[38:39], v[2:3] op_sel_hi:[1,0]
	v_pk_mul_f32 v[36:37], v[36:37], v[2:3] op_sel_hi:[1,0]
	v_pk_mul_f32 v[34:35], v[34:35], v[2:3] op_sel_hi:[1,0]
	v_pk_mul_f32 v[32:33], v[32:33], v[2:3] op_sel_hi:[1,0]
	v_pk_mul_f32 v[62:63], v[62:63], v[2:3] op_sel_hi:[1,0]
	v_pk_mul_f32 v[60:61], v[60:61], v[2:3] op_sel_hi:[1,0]
	v_pk_mul_f32 v[58:59], v[58:59], v[2:3] op_sel_hi:[1,0]
	v_pk_mul_f32 v[56:57], v[56:57], v[2:3] op_sel_hi:[1,0]
	v_pk_mul_f32 v[54:55], v[54:55], v[2:3] op_sel_hi:[1,0]
	v_pk_mul_f32 v[52:53], v[52:53], v[2:3] op_sel_hi:[1,0]
	v_pk_mul_f32 v[50:51], v[50:51], v[2:3] op_sel_hi:[1,0]
	v_pk_mul_f32 v[48:49], v[48:49], v[2:3] op_sel_hi:[1,0]
	v_mul_f32_e32 v161, v161, v2
	v_sub_f32_e32 v163, v163, v3
	v_sub_f32_e32 v82, v82, v3
	v_sub_f32_e32 v15, v15, v3
	v_sub_f32_e32 v84, v84, v3
	v_sub_f32_e32 v83, v83, v3
	v_sub_f32_e32 v86, v86, v3
	v_sub_f32_e32 v85, v85, v3
	v_sub_f32_e32 v88, v88, v3
	v_sub_f32_e32 v87, v87, v3
	v_sub_f32_e32 v90, v90, v3
	v_sub_f32_e32 v89, v89, v3
	v_sub_f32_e32 v92, v92, v3
	v_sub_f32_e32 v91, v91, v3
	v_sub_f32_e32 v80, v80, v3
	v_sub_f32_e32 v14, v14, v3
	v_sub_f32_e32 v79, v79, v3
	v_sub_f32_e32 v78, v78, v3
	v_sub_f32_e32 v77, v77, v3
	v_sub_f32_e32 v76, v76, v3
	v_sub_f32_e32 v75, v75, v3
	v_sub_f32_e32 v74, v74, v3
	v_sub_f32_e32 v73, v73, v3
	v_sub_f32_e32 v72, v72, v3
	v_sub_f32_e32 v71, v71, v3
	v_sub_f32_e32 v70, v70, v3
	v_sub_f32_e32 v69, v69, v3
	v_sub_f32_e32 v68, v68, v3
	v_sub_f32_e32 v67, v67, v3
	v_sub_f32_e32 v66, v66, v3
	v_sub_f32_e32 v65, v65, v3
	v_sub_f32_e32 v64, v64, v3
	v_mov_b32_e32 v17, v16
	v_mov_b32_e32 v18, v16
	v_mov_b32_e32 v19, v16
	v_mov_b32_e32 v20, v16
	v_mov_b32_e32 v21, v16
	v_mov_b32_e32 v22, v16
	v_mov_b32_e32 v23, v16
	v_mov_b32_e32 v24, v16
	v_mov_b32_e32 v25, v16
	v_mov_b32_e32 v26, v16
	v_mov_b32_e32 v27, v16
	v_mov_b32_e32 v28, v16
	v_mov_b32_e32 v29, v16
	v_mov_b32_e32 v30, v16
	v_mov_b32_e32 v31, v16

.LBB0_399:
	s_setprio 3
	s_add_i32 s34, s56, 0xfffc0000
	s_add_i32 s30, s55, -1
	s_and_b32 s34, s34, 0xf00000
	s_and_b32 s30, s30, 3
	s_lshl_b32 s78, s34, 1
	s_add_i32 s54, s29, 0
	v_lshl_add_u64 v[34:35], v[116:117], 0, s[78:79]
	s_mul_i32 s58, s30, 0x38000
	s_mov_b32 s59, s79
	s_add_i32 s34, s54, s5
	v_lshl_add_u64 v[34:35], v[34:35], 0, s[58:59]
	s_mov_b32 m0, s34
	s_add_i32 s35, s34, 0x2000
	global_load_lds_dwordx4 v[34:35], off
	v_lshl_add_u64 v[34:35], v[118:119], 0, s[78:79]
	v_lshl_add_u64 v[34:35], v[34:35], 0, s[58:59]
	s_mov_b32 m0, s35
	s_mov_b32 s30, s27
	global_load_lds_dwordx4 v[34:35], off
	s_mov_b32 s27, s72
	s_add_i32 s53, s30, 0
	v_add_u32_e32 v0, s53, v126
	ds_read_b128 v[34:37], v0
	ds_read_b128 v[38:41], v0 offset:2048
	v_exp_f32_e32 v145, v66
	v_exp_f32_e32 v146, v67
	v_exp_f32_e32 v147, v68
	v_exp_f32_e32 v148, v69
	v_exp_f32_e32 v149, v70
	v_exp_f32_e32 v150, v71
	v_exp_f32_e32 v151, v72
	s_waitcnt lgkmcnt(0)
	v_mfma_f32_32x32x16_bf16 v[82:97], v[34:37], v[110:113], v[50:65]
	ds_read_b128 v[34:37], v0 offset:4096
	v_exp_f32_e32 v152, v73
	v_exp_f32_e32 v153, v74
	v_exp_f32_e32 v154, v75
	v_exp_f32_e32 v155, v76
	s_setprio 2
	v_exp_f32_e32 v156, v77
	v_exp_f32_e32 v157, v78
	v_mfma_f32_32x32x16_bf16 v[82:97], v[38:41], v[106:109], v[82:97]
	ds_read_b128 v[38:41], v0 offset:6144
	v_exp_f32_e32 v158, v79
	v_exp_f32_e32 v159, v80
	v_exp_f32_e32 v160, v81
	s_waitcnt lgkmcnt(0)
	v_mfma_f32_32x32x16_bf16 v[82:97], v[34:37], v[102:105], v[82:97]
	v_add_f32_e32 v34, v129, v131
	v_add_f32_e32 v66, v132, v34
	ds_read_b128 v[34:37], v0 offset:512
	ds_read_b128 v[42:45], v0 offset:2560
	ds_read_b128 v[46:49], v0 offset:4608
	v_mfma_f32_32x32x16_bf16 v[82:97], v[38:41], v[98:101], v[82:97]
	ds_read_b128 v[38:41], v0 offset:6656
	v_add_f32_e32 v0, v135, v66
	v_add_f32_e32 v0, v136, v0
	v_add_f32_e32 v0, v139, v0
	v_add_f32_e32 v0, v140, v0
	v_add_f32_e32 v0, v143, v0
	v_add_f32_e32 v0, v130, v0
	s_waitcnt lgkmcnt(0)
	v_mfma_f32_32x32x16_bf16 v[66:81], v[34:37], v[110:113], v[50:65]
	v_add_f32_e32 v0, v133, v0
	v_add_f32_e32 v0, v134, v0
	v_add_f32_e32 v0, v137, v0
	v_add_f32_e32 v0, v138, v0
	v_add_f32_e32 v0, v141, v0
	v_add_f32_e32 v0, v142, v0
	v_add_f32_e32 v0, v144, v0
	v_mfma_f32_32x32x16_bf16 v[66:81], v[42:45], v[106:109], v[66:81]
	v_add_f32_e32 v0, v145, v0
	v_add_f32_e32 v0, v146, v0
	v_add_f32_e32 v0, v147, v0
	v_add_f32_e32 v0, v148, v0
	v_add_f32_e32 v0, v149, v0
	v_add_f32_e32 v0, v150, v0
	v_add_f32_e32 v0, v151, v0
	v_mfma_f32_32x32x16_bf16 v[66:81], v[46:49], v[102:105], v[66:81]
	v_add_f32_e32 v0, v152, v0
	v_add_f32_e32 v0, v153, v0
	v_add_f32_e32 v0, v154, v0
	v_add_f32_e32 v0, v155, v0
	v_add_f32_e32 v0, v156, v0
	v_add_f32_e32 v0, v157, v0
	v_add_f32_e32 v0, v158, v0
	v_mfma_f32_32x32x16_bf16 v[66:81], v[38:41], v[98:101], v[66:81]
	v_cvt_pk_bf16_f32 v34, v129, v131
	v_add_f32_e32 v161, v159, v0
	v_cvt_pk_bf16_f32 v35, v132, v135
	v_cvt_pk_bf16_f32 v36, v136, v139
	v_cvt_pk_bf16_f32 v37, v140, v143
	v_cvt_pk_bf16_f32 v38, v130, v133
	v_cvt_pk_bf16_f32 v39, v134, v137
	v_cvt_pk_bf16_f32 v40, v138, v141
	v_cvt_pk_bf16_f32 v41, v142, v144
	v_cvt_pk_bf16_f32 v42, v145, v146
	v_cvt_pk_bf16_f32 v43, v147, v148
	v_cvt_pk_bf16_f32 v44, v149, v150
	v_cvt_pk_bf16_f32 v45, v151, v152
	v_cvt_pk_bf16_f32 v46, v153, v154
	v_cvt_pk_bf16_f32 v47, v155, v156
	v_cvt_pk_bf16_f32 v48, v157, v158
	v_cvt_pk_bf16_f32 v49, v159, v160
	s_add_i32 s57, s72, 0
	v_add_u32_e32 v0, s57, v125
	ds_read_b64_tr_b16 v[130:131], v0 offset:8192
	ds_read_b64_tr_b16 v[132:133], v0 offset:8704
	s_setprio 1
	ds_read_b64_tr_b16 v[134:135], v0 offset:12288
	v_max_f32_e32 v129, v67, v67
	s_waitcnt lgkmcnt(1)
	v_mfma_f32_32x32x16_bf16 v[18:33], v[130:133], v[34:37], v[18:33]
	ds_read_b64_tr_b16 v[136:137], v0 offset:12800
	ds_read_b64_tr_b16 v[130:131], v0 offset:9216
	s_waitcnt lgkmcnt(1)
	v_mfma_f32_32x32x16_bf16 v[2:17], v[134:137], v[34:37], v[2:17]
	ds_read_b64_tr_b16 v[132:133], v0 offset:9728
	ds_read_b64_tr_b16 v[34:35], v0 offset:13312
	s_waitcnt lgkmcnt(1)
	v_mfma_f32_32x32x16_bf16 v[18:33], v[130:133], v[38:41], v[18:33]
	ds_read_b64_tr_b16 v[36:37], v0 offset:13824
	ds_read_b64_tr_b16 v[130:131], v0 offset:10240
	s_waitcnt lgkmcnt(1)
	v_mfma_f32_32x32x16_bf16 v[2:17], v[34:37], v[38:41], v[2:17]
	ds_read_b64_tr_b16 v[132:133], v0 offset:10752
	ds_read_b64_tr_b16 v[34:35], v0 offset:11264
	ds_read_b64_tr_b16 v[36:37], v0 offset:11776
	ds_read_b64_tr_b16 v[38:39], v0 offset:14336
	ds_read_b64_tr_b16 v[40:41], v0 offset:14848
	ds_read_b64_tr_b16 v[134:135], v0 offset:15360
	ds_read_b64_tr_b16 v[136:137], v0 offset:15872
	s_waitcnt lgkmcnt(6)
	v_mfma_f32_32x32x16_bf16 v[18:33], v[130:133], v[42:45], v[18:33]
	v_max_f32_e32 v130, v83, v83
	v_max_f32_e32 v129, v130, v129
	v_max3_f32 v130, v82, v66, v84
	v_max3_f32 v129, v129, v85, v69
	v_max3_f32 v130, v130, v68, v86
	v_max3_f32 v129, v129, v87, v71
	s_waitcnt lgkmcnt(2)
	v_mfma_f32_32x32x16_bf16 v[2:17], v[38:41], v[42:45], v[2:17]
	v_max3_f32 v38, v130, v70, v88
	v_max3_f32 v39, v129, v89, v73
	v_max3_f32 v38, v38, v72, v90
	v_max3_f32 v39, v39, v91, v75
	v_max3_f32 v38, v38, v74, v92
	v_max3_f32 v39, v39, v93, v77
	v_max3_f32 v38, v38, v76, v94
	v_mfma_f32_32x32x16_bf16 v[18:33], v[34:37], v[46:49], v[18:33]
	v_max3_f32 v34, v39, v95, v79
	v_max3_f32 v35, v38, v78, v96
	v_max3_f32 v34, v34, v97, v81
	v_add_f32_e32 v36, v160, v161
	v_max3_f32 v34, v35, v80, v34
	v_add_f32_e32 v128, v128, v36
	v_cmp_lt_f32_e32 vcc, s33, v34
	s_waitcnt lgkmcnt(0)
	v_mfma_f32_32x32x16_bf16 v[2:17], v[134:137], v[46:49], v[2:17]
	s_cbranch_vccz .LBB0_401
	v_mov_b32_e32 v35, v34
	s_nop 1
	v_permlane32_swap_b32 v34, v35
	s_nop 1
	s_nop 0
	v_max3_f32 v36, v34, v35, 0
	v_exp_f32_e64 v38, -v36
	v_add_f32_e32 v127, v127, v36
	v_xor_b32_e32 v34, 0x80000000, v127
	v_pk_add_f32 v[82:83], v[82:83], v[36:37] op_sel_hi:[1,0] neg_lo:[0,1] neg_hi:[0,1]
	v_pk_add_f32 v[66:67], v[66:67], v[36:37] op_sel_hi:[1,0] neg_lo:[0,1] neg_hi:[0,1]
	v_pk_add_f32 v[84:85], v[84:85], v[36:37] op_sel_hi:[1,0] neg_lo:[0,1] neg_hi:[0,1]
	v_pk_add_f32 v[68:69], v[68:69], v[36:37] op_sel_hi:[1,0] neg_lo:[0,1] neg_hi:[0,1]
	v_pk_add_f32 v[86:87], v[86:87], v[36:37] op_sel_hi:[1,0] neg_lo:[0,1] neg_hi:[0,1]
	v_pk_add_f32 v[70:71], v[70:71], v[36:37] op_sel_hi:[1,0] neg_lo:[0,1] neg_hi:[0,1]
	v_pk_add_f32 v[88:89], v[88:89], v[36:37] op_sel_hi:[1,0] neg_lo:[0,1] neg_hi:[0,1]
	v_pk_add_f32 v[72:73], v[72:73], v[36:37] op_sel_hi:[1,0] neg_lo:[0,1] neg_hi:[0,1]
	v_pk_add_f32 v[90:91], v[90:91], v[36:37] op_sel_hi:[1,0] neg_lo:[0,1] neg_hi:[0,1]
	v_pk_add_f32 v[74:75], v[74:75], v[36:37] op_sel_hi:[1,0] neg_lo:[0,1] neg_hi:[0,1]
	v_pk_add_f32 v[92:93], v[92:93], v[36:37] op_sel_hi:[1,0] neg_lo:[0,1] neg_hi:[0,1]
	v_pk_add_f32 v[76:77], v[76:77], v[36:37] op_sel_hi:[1,0] neg_lo:[0,1] neg_hi:[0,1]
	v_pk_add_f32 v[94:95], v[94:95], v[36:37] op_sel_hi:[1,0] neg_lo:[0,1] neg_hi:[0,1]
	v_pk_add_f32 v[78:79], v[78:79], v[36:37] op_sel_hi:[1,0] neg_lo:[0,1] neg_hi:[0,1]
	v_pk_add_f32 v[96:97], v[96:97], v[36:37] op_sel_hi:[1,0] neg_lo:[0,1] neg_hi:[0,1]
	v_pk_add_f32 v[80:81], v[80:81], v[36:37] op_sel_hi:[1,0] neg_lo:[0,1] neg_hi:[0,1]
	v_pk_mul_f32 v[32:33], v[32:33], v[38:39] op_sel_hi:[1,0]
	v_pk_mul_f32 v[30:31], v[30:31], v[38:39] op_sel_hi:[1,0]
	v_pk_mul_f32 v[28:29], v[28:29], v[38:39] op_sel_hi:[1,0]
	v_pk_mul_f32 v[26:27], v[26:27], v[38:39] op_sel_hi:[1,0]
	v_pk_mul_f32 v[24:25], v[24:25], v[38:39] op_sel_hi:[1,0]
	v_pk_mul_f32 v[22:23], v[22:23], v[38:39] op_sel_hi:[1,0]
	v_pk_mul_f32 v[20:21], v[20:21], v[38:39] op_sel_hi:[1,0]
	v_pk_mul_f32 v[18:19], v[18:19], v[38:39] op_sel_hi:[1,0]
	v_pk_mul_f32 v[16:17], v[16:17], v[38:39] op_sel_hi:[1,0]
	v_pk_mul_f32 v[14:15], v[14:15], v[38:39] op_sel_hi:[1,0]
	v_pk_mul_f32 v[12:13], v[12:13], v[38:39] op_sel_hi:[1,0]
	v_pk_mul_f32 v[10:11], v[10:11], v[38:39] op_sel_hi:[1,0]
	v_pk_mul_f32 v[8:9], v[8:9], v[38:39] op_sel_hi:[1,0]
	v_pk_mul_f32 v[6:7], v[6:7], v[38:39] op_sel_hi:[1,0]
	v_pk_mul_f32 v[4:5], v[4:5], v[38:39] op_sel_hi:[1,0]
	v_pk_mul_f32 v[2:3], v[2:3], v[38:39] op_sel_hi:[1,0]
	v_mul_f32_e32 v128, v128, v38
	v_mov_b32_e32 v35, v34
	v_mov_b32_e32 v36, v34
	v_mov_b32_e32 v37, v34
	v_mov_b32_e32 v38, v34
	v_mov_b32_e32 v39, v34
	v_mov_b32_e32 v40, v34
	v_mov_b32_e32 v41, v34
	v_mov_b32_e32 v42, v34
	v_mov_b32_e32 v43, v34
	v_mov_b32_e32 v44, v34
	v_mov_b32_e32 v45, v34
	v_mov_b32_e32 v46, v34
	v_mov_b32_e32 v47, v34
	v_mov_b32_e32 v48, v34
	v_mov_b32_e32 v49, v34
	v_mov_b32_e32 v50, v34
	v_mov_b32_e32 v51, v34
	v_mov_b32_e32 v52, v34
	v_mov_b32_e32 v53, v34
	v_mov_b32_e32 v54, v34
	v_mov_b32_e32 v55, v34
	v_mov_b32_e32 v56, v34
	v_mov_b32_e32 v57, v34
	v_mov_b32_e32 v58, v34
	v_mov_b32_e32 v59, v34
	v_mov_b32_e32 v60, v34
	v_mov_b32_e32 v61, v34
	v_mov_b32_e32 v62, v34
	v_mov_b32_e32 v63, v34
	v_mov_b32_e32 v64, v34
	v_mov_b32_e32 v65, v34
	s_branch .LBB0_402

.LBB0_402:
	v_exp_f32_e32 v129, v82
	s_setprio 0
	v_exp_f32_e32 v146, v83
	v_exp_f32_e32 v147, v84
	v_exp_f32_e32 v148, v85
	v_exp_f32_e32 v149, v86
	v_exp_f32_e32 v150, v87
	v_exp_f32_e32 v151, v88
	v_exp_f32_e32 v152, v89
	v_exp_f32_e32 v153, v90
	v_exp_f32_e32 v154, v91
	v_exp_f32_e32 v155, v92
	v_exp_f32_e32 v156, v93
	v_exp_f32_e32 v157, v94
	v_exp_f32_e32 v158, v95
	v_exp_f32_e32 v159, v96
	v_exp_f32_e32 v160, v97
	s_add_i32 s58, s55, 4
	s_and_b32 s59, s56, 0xf00000
	s_and_b32 s58, s58, 3
	s_lshl_b32 s78, s59, 1
	v_lshl_add_u64 v[82:83], v[116:117], 0, s[78:79]
	s_mul_i32 s58, s58, 0x38000
	s_mov_b32 s59, s79
	s_add_i32 s60, s57, s5
	v_lshl_add_u64 v[82:83], v[82:83], 0, s[58:59]
	s_mov_b32 m0, s60
	s_waitcnt vmcnt(0)
	s_barrier
	s_setprio 3
	global_load_lds_dwordx4 v[82:83], off
	v_lshl_add_u64 v[82:83], v[118:119], 0, s[78:79]
	v_lshl_add_u64 v[82:83], v[82:83], 0, s[58:59]
	s_add_i32 m0, s60, 0x2000
	s_nop 0
	global_load_lds_dwordx4 v[82:83], off
	v_add_u32_e32 v142, s54, v126
	ds_read_b128 v[130:133], v142
	ds_read_b128 v[134:137], v142 offset:2048
	v_exp_f32_e32 v161, v66
	v_exp_f32_e32 v162, v67
	v_exp_f32_e32 v163, v68
	v_exp_f32_e32 v164, v69
	ds_read_b128 v[66:69], v142 offset:4096
	v_exp_f32_e32 v165, v70
	v_exp_f32_e32 v166, v71
	s_waitcnt lgkmcnt(0)
	v_mfma_f32_32x32x16_bf16 v[82:97], v[130:133], v[110:113], v[34:49]
	v_exp_f32_e32 v167, v72
	v_exp_f32_e32 v168, v73
	ds_read_b128 v[70:73], v142 offset:6144
	v_exp_f32_e32 v169, v74
	v_exp_f32_e32 v170, v75
	v_exp_f32_e32 v171, v76
	v_exp_f32_e32 v172, v77
	v_mfma_f32_32x32x16_bf16 v[82:97], v[134:137], v[106:109], v[82:97]
	ds_read_b128 v[130:133], v142 offset:512
	ds_read_b128 v[134:137], v142 offset:2560
	ds_read_b128 v[138:141], v142 offset:4608
	ds_read_b128 v[142:145], v142 offset:6656
	v_exp_f32_e32 v173, v78
	v_exp_f32_e32 v174, v79
	v_exp_f32_e32 v175, v80
	v_exp_f32_e32 v176, v81
	v_mfma_f32_32x32x16_bf16 v[82:97], v[66:69], v[102:105], v[82:97]
	v_add_f32_e32 v66, v129, v146
	s_setprio 2
	v_add_f32_e32 v66, v147, v66
	v_add_f32_e32 v66, v148, v66
	v_add_f32_e32 v66, v149, v66
	v_add_f32_e32 v66, v150, v66
	v_add_f32_e32 v66, v151, v66
	v_add_f32_e32 v66, v152, v66
	v_add_f32_e32 v66, v153, v66
	s_waitcnt lgkmcnt(0)
	v_mfma_f32_32x32x16_bf16 v[82:97], v[70:73], v[98:101], v[82:97]
	v_add_f32_e32 v177, v154, v66
	v_mfma_f32_32x32x16_bf16 v[66:81], v[130:133], v[110:113], v[34:49]
	v_add_f32_e32 v130, v155, v177
	v_add_f32_e32 v130, v156, v130
	v_add_f32_e32 v130, v157, v130
	v_add_f32_e32 v130, v158, v130
	v_add_f32_e32 v130, v159, v130
	v_add_f32_e32 v130, v160, v130
	v_add_f32_e32 v130, v161, v130
	v_mfma_f32_32x32x16_bf16 v[66:81], v[134:137], v[106:109], v[66:81]
	v_add_f32_e32 v130, v162, v130
	v_add_f32_e32 v130, v163, v130
	v_add_f32_e32 v130, v164, v130
	v_add_f32_e32 v130, v165, v130
	v_add_f32_e32 v130, v166, v130
	v_add_f32_e32 v130, v167, v130
	v_add_f32_e32 v130, v168, v130
	v_mfma_f32_32x32x16_bf16 v[66:81], v[138:141], v[102:105], v[66:81]
	v_add_f32_e32 v130, v169, v130
	v_add_f32_e32 v130, v170, v130
	v_add_f32_e32 v130, v171, v130
	v_add_f32_e32 v130, v172, v130
	v_add_f32_e32 v130, v173, v130
	v_add_f32_e32 v130, v174, v130
	v_add_f32_e32 v177, v175, v130
	v_mfma_f32_32x32x16_bf16 v[66:81], v[142:145], v[98:101], v[66:81]
	v_cvt_pk_bf16_f32 v130, v129, v146
	v_cvt_pk_bf16_f32 v131, v147, v148
	v_cvt_pk_bf16_f32 v132, v149, v150
	v_cvt_pk_bf16_f32 v133, v151, v152
	v_cvt_pk_bf16_f32 v134, v153, v154
	v_cvt_pk_bf16_f32 v135, v155, v156
	v_cvt_pk_bf16_f32 v136, v157, v158
	v_cvt_pk_bf16_f32 v137, v159, v160
	v_cvt_pk_bf16_f32 v138, v161, v162
	v_cvt_pk_bf16_f32 v139, v163, v164
	v_cvt_pk_bf16_f32 v140, v165, v166
	v_cvt_pk_bf16_f32 v141, v167, v168
	v_cvt_pk_bf16_f32 v142, v169, v170
	v_cvt_pk_bf16_f32 v143, v171, v172
	v_cvt_pk_bf16_f32 v144, v173, v174
	v_cvt_pk_bf16_f32 v145, v175, v176
	v_add_u32_e32 v129, s53, v125
	ds_read_b64_tr_b16 v[146:147], v129 offset:8192
	ds_read_b64_tr_b16 v[148:149], v129 offset:8704
	ds_read_b64_tr_b16 v[150:151], v129 offset:12288
	s_waitcnt lgkmcnt(1)
	v_mfma_f32_32x32x16_bf16 v[18:33], v[146:149], v[130:133], v[18:33]
	ds_read_b64_tr_b16 v[152:153], v129 offset:12800
	ds_read_b64_tr_b16 v[146:147], v129 offset:9216
	s_waitcnt lgkmcnt(1)
	v_mfma_f32_32x32x16_bf16 v[2:17], v[150:153], v[130:133], v[2:17]
	ds_read_b64_tr_b16 v[148:149], v129 offset:9728
	s_setprio 1
	ds_read_b64_tr_b16 v[130:131], v129 offset:13312
	s_waitcnt lgkmcnt(1)
	v_mfma_f32_32x32x16_bf16 v[18:33], v[146:149], v[134:137], v[18:33]
	ds_read_b64_tr_b16 v[132:133], v129 offset:13824
	ds_read_b64_tr_b16 v[146:147], v129 offset:10240
	s_waitcnt lgkmcnt(1)
	v_mfma_f32_32x32x16_bf16 v[2:17], v[130:133], v[134:137], v[2:17]
	ds_read_b64_tr_b16 v[148:149], v129 offset:10752
	ds_read_b64_tr_b16 v[130:131], v129 offset:11264
	ds_read_b64_tr_b16 v[132:133], v129 offset:11776
	ds_read_b64_tr_b16 v[134:135], v129 offset:14336
	ds_read_b64_tr_b16 v[136:137], v129 offset:14848
	ds_read_b64_tr_b16 v[150:151], v129 offset:15360
	ds_read_b64_tr_b16 v[152:153], v129 offset:15872
	v_max_f32_e32 v129, v67, v67
	s_waitcnt lgkmcnt(6)
	v_mfma_f32_32x32x16_bf16 v[18:33], v[146:149], v[138:141], v[18:33]
	v_max_f32_e32 v146, v83, v83
	v_max_f32_e32 v129, v146, v129
	v_max3_f32 v146, v82, v66, v84
	v_max3_f32 v129, v129, v85, v69
	v_max3_f32 v146, v146, v68, v86
	v_max3_f32 v129, v129, v87, v71
	v_max3_f32 v129, v129, v89, v73
	s_waitcnt lgkmcnt(2)
	v_mfma_f32_32x32x16_bf16 v[2:17], v[134:137], v[138:141], v[2:17]
	v_max3_f32 v134, v146, v70, v88
	v_max3_f32 v134, v134, v72, v90
	v_max3_f32 v129, v129, v91, v75
	v_max3_f32 v134, v134, v74, v92
	v_max3_f32 v129, v129, v93, v77
	v_max3_f32 v134, v134, v76, v94
	v_max3_f32 v129, v129, v95, v79
	v_mfma_f32_32x32x16_bf16 v[18:33], v[130:133], v[142:145], v[18:33]
	v_max3_f32 v130, v134, v78, v96
	v_max3_f32 v129, v129, v97, v81
	v_add_f32_e32 v131, v176, v177
	v_max3_f32 v129, v130, v80, v129
	v_add_f32_e32 v128, v128, v131
	v_cmp_lt_f32_e32 vcc, s33, v129
	s_waitcnt lgkmcnt(0)
	v_mfma_f32_32x32x16_bf16 v[2:17], v[150:153], v[142:145], v[2:17]
	s_cbranch_vccz .LBB0_404
	v_mov_b32_e32 v34, v129
	s_nop 1
	v_permlane32_swap_b32 v129, v34
	s_nop 1
	s_nop 0
	v_max3_f32 v36, v129, v34, 0
	v_exp_f32_e64 v38, -v36
	v_add_f32_e32 v127, v127, v36
	v_xor_b32_e32 v34, 0x80000000, v127
	v_pk_add_f32 v[82:83], v[82:83], v[36:37] op_sel_hi:[1,0] neg_lo:[0,1] neg_hi:[0,1]
	v_pk_add_f32 v[84:85], v[84:85], v[36:37] op_sel_hi:[1,0] neg_lo:[0,1] neg_hi:[0,1]
	v_pk_add_f32 v[86:87], v[86:87], v[36:37] op_sel_hi:[1,0] neg_lo:[0,1] neg_hi:[0,1]
	v_pk_add_f32 v[88:89], v[88:89], v[36:37] op_sel_hi:[1,0] neg_lo:[0,1] neg_hi:[0,1]
	v_pk_add_f32 v[90:91], v[90:91], v[36:37] op_sel_hi:[1,0] neg_lo:[0,1] neg_hi:[0,1]
	v_pk_add_f32 v[92:93], v[92:93], v[36:37] op_sel_hi:[1,0] neg_lo:[0,1] neg_hi:[0,1]
	v_pk_add_f32 v[94:95], v[94:95], v[36:37] op_sel_hi:[1,0] neg_lo:[0,1] neg_hi:[0,1]
	v_pk_add_f32 v[96:97], v[96:97], v[36:37] op_sel_hi:[1,0] neg_lo:[0,1] neg_hi:[0,1]
	v_sub_f32_e32 v81, v81, v36
	v_sub_f32_e32 v80, v80, v36
	v_sub_f32_e32 v79, v79, v36
	v_sub_f32_e32 v78, v78, v36
	v_sub_f32_e32 v77, v77, v36
	v_sub_f32_e32 v76, v76, v36
	v_sub_f32_e32 v75, v75, v36
	v_sub_f32_e32 v74, v74, v36
	v_sub_f32_e32 v73, v73, v36
	v_sub_f32_e32 v72, v72, v36
	v_sub_f32_e32 v71, v71, v36
	v_sub_f32_e32 v70, v70, v36
	v_sub_f32_e32 v69, v69, v36
	v_sub_f32_e32 v68, v68, v36
	v_sub_f32_e32 v67, v67, v36
	v_sub_f32_e32 v66, v66, v36
	v_pk_mul_f32 v[32:33], v[32:33], v[38:39] op_sel_hi:[1,0]
	v_pk_mul_f32 v[30:31], v[30:31], v[38:39] op_sel_hi:[1,0]
	v_pk_mul_f32 v[28:29], v[28:29], v[38:39] op_sel_hi:[1,0]
	v_pk_mul_f32 v[26:27], v[26:27], v[38:39] op_sel_hi:[1,0]
	v_pk_mul_f32 v[24:25], v[24:25], v[38:39] op_sel_hi:[1,0]
	v_pk_mul_f32 v[22:23], v[22:23], v[38:39] op_sel_hi:[1,0]
	v_pk_mul_f32 v[20:21], v[20:21], v[38:39] op_sel_hi:[1,0]
	v_pk_mul_f32 v[18:19], v[18:19], v[38:39] op_sel_hi:[1,0]
	v_pk_mul_f32 v[16:17], v[16:17], v[38:39] op_sel_hi:[1,0]
	v_pk_mul_f32 v[14:15], v[14:15], v[38:39] op_sel_hi:[1,0]
	v_pk_mul_f32 v[12:13], v[12:13], v[38:39] op_sel_hi:[1,0]
	v_pk_mul_f32 v[10:11], v[10:11], v[38:39] op_sel_hi:[1,0]
	v_pk_mul_f32 v[8:9], v[8:9], v[38:39] op_sel_hi:[1,0]
	v_pk_mul_f32 v[6:7], v[6:7], v[38:39] op_sel_hi:[1,0]
	v_pk_mul_f32 v[4:5], v[4:5], v[38:39] op_sel_hi:[1,0]
	v_pk_mul_f32 v[2:3], v[2:3], v[38:39] op_sel_hi:[1,0]
	v_mul_f32_e32 v128, v128, v38
	v_mov_b32_e32 v35, v34
	v_mov_b32_e32 v36, v34
	v_mov_b32_e32 v37, v34
	v_mov_b32_e32 v38, v34
	v_mov_b32_e32 v39, v34
	v_mov_b32_e32 v40, v34
	v_mov_b32_e32 v41, v34
	v_mov_b32_e32 v42, v34
	v_mov_b32_e32 v43, v34
	v_mov_b32_e32 v44, v34
	v_mov_b32_e32 v45, v34
	v_mov_b32_e32 v46, v34
	v_mov_b32_e32 v47, v34
	v_mov_b32_e32 v48, v34
	v_mov_b32_e32 v49, v34
	v_mov_b32_e32 v50, v34
	v_mov_b32_e32 v51, v34
	v_mov_b32_e32 v52, v34
	v_mov_b32_e32 v53, v34
	v_mov_b32_e32 v54, v34
	v_mov_b32_e32 v55, v34
	v_mov_b32_e32 v56, v34
	v_mov_b32_e32 v57, v34
	v_mov_b32_e32 v58, v34
	v_mov_b32_e32 v59, v34
	v_mov_b32_e32 v60, v34
	v_mov_b32_e32 v61, v34
	v_mov_b32_e32 v62, v34
	v_mov_b32_e32 v63, v34
	v_mov_b32_e32 v64, v34
	v_mov_b32_e32 v65, v34

.LBB0_424:
	s_lshl_b32 s55, s55, 15
	v_lshl_add_u64 v[34:35], v[130:131], 0, s[78:79]
	s_lshl_b32 s78, s55, 1
	v_lshl_add_u64 v[34:35], v[34:35], 0, s[78:79]
	s_add_i32 s55, s54, 0x3000
	v_lshl_add_u64 v[34:35], v[34:35], 0, s[24:25]
	s_mov_b32 m0, s55
	s_nop 0
	global_load_lds_dwordx4 v[34:35], off
	s_add_i32 s56, s30, 0
	v_add_u32_e32 v0, s56, v134
	ds_read_b128 v[34:37], v0
	s_setprio 2
	v_exp_f32_e32 v153, v66
	v_exp_f32_e32 v166, v67
	v_exp_f32_e32 v167, v68
	v_exp_f32_e32 v168, v69
	v_exp_f32_e32 v169, v70
	v_exp_f32_e32 v170, v71
	v_exp_f32_e32 v171, v72
	v_exp_f32_e32 v172, v73
	s_waitcnt lgkmcnt(0)
	v_mfma_f32_32x32x16_bf16 v[82:97], v[34:37], v[118:121], v[50:65]
	ds_read_b128 v[34:37], v0 offset:2048
	ds_read_b128 v[38:41], v0 offset:4096
	v_exp_f32_e32 v173, v74
	v_exp_f32_e32 v174, v75
	v_exp_f32_e32 v175, v76
	v_exp_f32_e32 v176, v77
	v_exp_f32_e32 v177, v78
	v_exp_f32_e32 v178, v79
	s_waitcnt lgkmcnt(0)
	v_mfma_f32_32x32x16_bf16 v[82:97], v[34:37], v[114:117], v[82:97]
	ds_read_b128 v[34:37], v0 offset:6144
	v_exp_f32_e32 v179, v80
	v_exp_f32_e32 v180, v81
	v_mfma_f32_32x32x16_bf16 v[82:97], v[38:41], v[110:113], v[82:97]
	ds_read_b128 v[38:41], v0 offset:8192
	s_waitcnt lgkmcnt(0)
	v_mfma_f32_32x32x16_bf16 v[82:97], v[34:37], v[106:109], v[82:97]
	v_add_f32_e32 v34, v141, v146
	v_add_f32_e32 v66, v138, v34
	ds_read_b128 v[34:37], v0 offset:10240
	v_mfma_f32_32x32x16_bf16 v[82:97], v[38:41], v[102:105], v[82:97]
	ds_read_b128 v[38:41], v0 offset:512
	ds_read_b128 v[42:45], v0 offset:2560
	ds_read_b128 v[46:49], v0 offset:4608
	ds_read_b128 v[154:157], v0 offset:6656
	ds_read_b128 v[158:161], v0 offset:8704
	ds_read_b128 v[162:165], v0 offset:10752
	v_add_f32_e32 v0, v142, v66
	v_add_f32_e32 v0, v143, v0
	v_add_f32_e32 v0, v147, v0
	v_add_f32_e32 v0, v148, v0
	v_add_f32_e32 v0, v151, v0
	v_add_f32_e32 v0, v137, v0
	s_waitcnt lgkmcnt(0)
	v_mfma_f32_32x32x16_bf16 v[66:81], v[38:41], v[118:121], v[50:65]
	v_add_f32_e32 v0, v139, v0
	v_add_f32_e32 v0, v140, v0
	v_add_f32_e32 v0, v144, v0
	v_add_f32_e32 v0, v145, v0
	v_add_f32_e32 v0, v149, v0
	v_add_f32_e32 v0, v150, v0
	v_add_f32_e32 v0, v152, v0
	v_mfma_f32_32x32x16_bf16 v[66:81], v[42:45], v[114:117], v[66:81]
	v_add_f32_e32 v0, v153, v0
	v_add_f32_e32 v0, v166, v0
	v_add_f32_e32 v0, v167, v0
	v_add_f32_e32 v0, v168, v0
	v_add_f32_e32 v0, v169, v0
	v_add_f32_e32 v0, v170, v0
	v_add_f32_e32 v0, v171, v0
	v_mfma_f32_32x32x16_bf16 v[66:81], v[46:49], v[110:113], v[66:81]
	v_add_f32_e32 v0, v172, v0
	v_add_f32_e32 v0, v173, v0
	v_add_f32_e32 v0, v174, v0
	v_add_f32_e32 v0, v175, v0
	v_add_f32_e32 v0, v176, v0
	v_add_f32_e32 v0, v177, v0
	v_add_f32_e32 v0, v178, v0
	v_mfma_f32_32x32x16_bf16 v[66:81], v[154:157], v[106:109], v[66:81]
	v_add_f32_e32 v181, v179, v0
	v_cvt_pk_bf16_f32 v38, v137, v139
	v_cvt_pk_bf16_f32 v39, v140, v144
	v_cvt_pk_bf16_f32 v40, v145, v149
	v_cvt_pk_bf16_f32 v41, v150, v152
	v_cvt_pk_bf16_f32 v42, v153, v166
	s_setprio 1
	v_cvt_pk_bf16_f32 v43, v167, v168
	v_mfma_f32_32x32x16_bf16 v[66:81], v[158:161], v[102:105], v[66:81]
	v_cvt_pk_bf16_f32 v44, v169, v170
	v_cvt_pk_bf16_f32 v45, v171, v172
	v_cvt_pk_bf16_f32 v46, v173, v174
	v_cvt_pk_bf16_f32 v47, v175, v176
	v_cvt_pk_bf16_f32 v48, v177, v178
	v_cvt_pk_bf16_f32 v49, v179, v180
	v_mfma_f32_32x32x16_bf16 v[82:97], v[34:37], v[98:101], v[82:97]
	v_cvt_pk_bf16_f32 v34, v141, v146
	v_cvt_pk_bf16_f32 v35, v138, v142
	v_cvt_pk_bf16_f32 v36, v143, v147
	v_cvt_pk_bf16_f32 v37, v148, v151
	v_mfma_f32_32x32x16_bf16 v[66:81], v[162:165], v[98:101], v[66:81]
	s_add_i32 s59, s28, 0
	v_add_u32_e32 v0, s59, v133
	ds_read_b64_tr_b16 v[138:139], v0 offset:12288
	ds_read_b64_tr_b16 v[140:141], v0 offset:12800
	ds_read_b64_tr_b16 v[142:143], v0 offset:16384
	s_nop 5
	v_max_f32_e32 v137, v67, v67
	s_waitcnt lgkmcnt(1)
	v_mfma_f32_32x32x16_bf16 v[18:33], v[138:141], v[34:37], v[18:33]
	ds_read_b64_tr_b16 v[144:145], v0 offset:16896
	ds_read_b64_tr_b16 v[138:139], v0 offset:13312
	s_waitcnt lgkmcnt(1)
	v_mfma_f32_32x32x16_bf16 v[2:17], v[142:145], v[34:37], v[2:17]
	ds_read_b64_tr_b16 v[140:141], v0 offset:13824
	ds_read_b64_tr_b16 v[34:35], v0 offset:17408
	s_waitcnt lgkmcnt(1)
	v_mfma_f32_32x32x16_bf16 v[18:33], v[138:141], v[38:41], v[18:33]
	ds_read_b64_tr_b16 v[36:37], v0 offset:17920
	ds_read_b64_tr_b16 v[138:139], v0 offset:14336
	s_waitcnt lgkmcnt(1)
	v_mfma_f32_32x32x16_bf16 v[2:17], v[34:37], v[38:41], v[2:17]
	ds_read_b64_tr_b16 v[140:141], v0 offset:14848
	ds_read_b64_tr_b16 v[34:35], v0 offset:15360
	ds_read_b64_tr_b16 v[36:37], v0 offset:15872
	ds_read_b64_tr_b16 v[38:39], v0 offset:18432
	ds_read_b64_tr_b16 v[40:41], v0 offset:18944
	ds_read_b64_tr_b16 v[142:143], v0 offset:19456
	ds_read_b64_tr_b16 v[144:145], v0 offset:19968
	s_waitcnt lgkmcnt(6)
	v_mfma_f32_32x32x16_bf16 v[18:33], v[138:141], v[42:45], v[18:33]
	v_max_f32_e32 v138, v83, v83
	v_max_f32_e32 v137, v138, v137
	v_max3_f32 v138, v82, v66, v84
	v_max3_f32 v137, v137, v85, v69
	v_max3_f32 v138, v138, v68, v86
	v_max3_f32 v137, v137, v87, v71
	s_waitcnt lgkmcnt(2)
	v_mfma_f32_32x32x16_bf16 v[2:17], v[38:41], v[42:45], v[2:17]
	v_max3_f32 v38, v138, v70, v88
	v_max3_f32 v39, v137, v89, v73
	v_max3_f32 v38, v38, v72, v90
	v_max3_f32 v39, v39, v91, v75
	v_max3_f32 v38, v38, v74, v92
	v_max3_f32 v39, v39, v93, v77
	v_max3_f32 v38, v38, v76, v94
	v_mfma_f32_32x32x16_bf16 v[18:33], v[34:37], v[46:49], v[18:33]
	v_max3_f32 v34, v39, v95, v79
	v_max3_f32 v35, v38, v78, v96
	v_max3_f32 v34, v34, v97, v81
	v_add_f32_e32 v36, v180, v181
	v_max3_f32 v34, v35, v80, v34
	v_add_f32_e32 v136, v136, v36
	v_cmp_lt_f32_e32 vcc, s33, v34
	s_waitcnt lgkmcnt(0)
	v_mfma_f32_32x32x16_bf16 v[2:17], v[142:145], v[46:49], v[2:17]
	s_cbranch_vccz .LBB0_426
	v_mov_b32_e32 v35, v34
	s_nop 1
	v_permlane32_swap_b32 v34, v35
	s_nop 1
	s_nop 0
	v_max3_f32 v36, v34, v35, 0
	v_exp_f32_e64 v38, -v36
	v_add_f32_e32 v135, v135, v36
	v_xor_b32_e32 v34, 0x80000000, v135
	v_pk_add_f32 v[82:83], v[82:83], v[36:37] op_sel_hi:[1,0] neg_lo:[0,1] neg_hi:[0,1]
	v_pk_add_f32 v[84:85], v[84:85], v[36:37] op_sel_hi:[1,0] neg_lo:[0,1] neg_hi:[0,1]
	v_pk_add_f32 v[86:87], v[86:87], v[36:37] op_sel_hi:[1,0] neg_lo:[0,1] neg_hi:[0,1]
	v_pk_add_f32 v[88:89], v[88:89], v[36:37] op_sel_hi:[1,0] neg_lo:[0,1] neg_hi:[0,1]
	v_pk_add_f32 v[90:91], v[90:91], v[36:37] op_sel_hi:[1,0] neg_lo:[0,1] neg_hi:[0,1]
	v_pk_add_f32 v[92:93], v[92:93], v[36:37] op_sel_hi:[1,0] neg_lo:[0,1] neg_hi:[0,1]
	v_pk_add_f32 v[94:95], v[94:95], v[36:37] op_sel_hi:[1,0] neg_lo:[0,1] neg_hi:[0,1]
	v_pk_add_f32 v[96:97], v[96:97], v[36:37] op_sel_hi:[1,0] neg_lo:[0,1] neg_hi:[0,1]
	v_sub_f32_e32 v81, v81, v36
	v_sub_f32_e32 v80, v80, v36
	v_sub_f32_e32 v79, v79, v36
	v_sub_f32_e32 v78, v78, v36
	v_sub_f32_e32 v77, v77, v36
	v_sub_f32_e32 v76, v76, v36
	v_sub_f32_e32 v75, v75, v36
	v_sub_f32_e32 v74, v74, v36
	v_sub_f32_e32 v73, v73, v36
	v_sub_f32_e32 v72, v72, v36
	v_sub_f32_e32 v71, v71, v36
	v_sub_f32_e32 v70, v70, v36
	v_sub_f32_e32 v69, v69, v36
	v_sub_f32_e32 v68, v68, v36
	v_sub_f32_e32 v67, v67, v36
	v_sub_f32_e32 v66, v66, v36
	v_pk_mul_f32 v[32:33], v[32:33], v[38:39] op_sel_hi:[1,0]
	v_pk_mul_f32 v[30:31], v[30:31], v[38:39] op_sel_hi:[1,0]
	v_pk_mul_f32 v[28:29], v[28:29], v[38:39] op_sel_hi:[1,0]
	v_pk_mul_f32 v[26:27], v[26:27], v[38:39] op_sel_hi:[1,0]
	v_pk_mul_f32 v[24:25], v[24:25], v[38:39] op_sel_hi:[1,0]
	v_pk_mul_f32 v[22:23], v[22:23], v[38:39] op_sel_hi:[1,0]
	v_pk_mul_f32 v[20:21], v[20:21], v[38:39] op_sel_hi:[1,0]
	v_pk_mul_f32 v[18:19], v[18:19], v[38:39] op_sel_hi:[1,0]
	v_pk_mul_f32 v[16:17], v[16:17], v[38:39] op_sel_hi:[1,0]
	v_pk_mul_f32 v[14:15], v[14:15], v[38:39] op_sel_hi:[1,0]
	v_pk_mul_f32 v[12:13], v[12:13], v[38:39] op_sel_hi:[1,0]
	v_pk_mul_f32 v[10:11], v[10:11], v[38:39] op_sel_hi:[1,0]
	v_pk_mul_f32 v[8:9], v[8:9], v[38:39] op_sel_hi:[1,0]
	v_pk_mul_f32 v[6:7], v[6:7], v[38:39] op_sel_hi:[1,0]
	v_pk_mul_f32 v[4:5], v[4:5], v[38:39] op_sel_hi:[1,0]
	v_pk_mul_f32 v[2:3], v[2:3], v[38:39] op_sel_hi:[1,0]
	v_mul_f32_e32 v136, v136, v38
	v_mov_b32_e32 v35, v34
	v_mov_b32_e32 v36, v34
	v_mov_b32_e32 v37, v34
	v_mov_b32_e32 v38, v34
	v_mov_b32_e32 v39, v34
	v_mov_b32_e32 v40, v34
	v_mov_b32_e32 v41, v34
	v_mov_b32_e32 v42, v34
	v_mov_b32_e32 v43, v34
	v_mov_b32_e32 v44, v34
	v_mov_b32_e32 v45, v34
	v_mov_b32_e32 v46, v34
	v_mov_b32_e32 v47, v34
	v_mov_b32_e32 v48, v34
	v_mov_b32_e32 v49, v34
	v_mov_b32_e32 v50, v34
	v_mov_b32_e32 v51, v34
	v_mov_b32_e32 v52, v34
	v_mov_b32_e32 v53, v34
	v_mov_b32_e32 v54, v34
	v_mov_b32_e32 v55, v34
	v_mov_b32_e32 v56, v34
	v_mov_b32_e32 v57, v34
	v_mov_b32_e32 v58, v34
	v_mov_b32_e32 v59, v34
	v_mov_b32_e32 v60, v34
	v_mov_b32_e32 v61, v34
	v_mov_b32_e32 v62, v34
	v_mov_b32_e32 v63, v34
	v_mov_b32_e32 v64, v34
	v_mov_b32_e32 v65, v34
	s_branch .LBB0_427

.LBB0_429:
	s_lshl_b32 s40, s60, 15
	v_exp_f32_e32 v137, v82
	v_exp_f32_e32 v162, v83
	v_lshl_add_u64 v[82:83], v[130:131], 0, s[78:79]
	s_lshl_b32 s78, s40, 1
	v_lshl_add_u64 v[82:83], v[82:83], 0, s[78:79]
	v_lshl_add_u64 v[82:83], v[82:83], 0, s[24:25]
	s_add_i32 m0, s61, 0x3000
	v_exp_f32_e32 v163, v84
	global_load_lds_dwordx4 v[82:83], off
	v_exp_f32_e32 v164, v85
	v_exp_f32_e32 v165, v86
	v_exp_f32_e32 v166, v87
	v_exp_f32_e32 v167, v88
	v_exp_f32_e32 v168, v89
	v_exp_f32_e32 v169, v90
	v_exp_f32_e32 v170, v91
	v_exp_f32_e32 v171, v92
	v_exp_f32_e32 v172, v93
	v_exp_f32_e32 v173, v94
	v_exp_f32_e32 v174, v95
	v_exp_f32_e32 v175, v96
	v_exp_f32_e32 v176, v97
	v_add_u32_e32 v158, s53, v134
	ds_read_b128 v[138:141], v158
	v_exp_f32_e32 v177, v66
	v_exp_f32_e32 v178, v67
	v_exp_f32_e32 v179, v68
	v_exp_f32_e32 v180, v69
	s_setprio 2
	v_exp_f32_e32 v181, v70
	v_exp_f32_e32 v182, v71
	v_exp_f32_e32 v183, v72
	v_exp_f32_e32 v184, v73
	s_waitcnt lgkmcnt(0)
	v_mfma_f32_32x32x16_bf16 v[82:97], v[138:141], v[118:121], v[34:49]
	ds_read_b128 v[138:141], v158 offset:2048
	ds_read_b128 v[142:145], v158 offset:4096
	ds_read_b128 v[66:69], v158 offset:6144
	ds_read_b128 v[70:73], v158 offset:8192
	v_exp_f32_e32 v185, v74
	v_add_f32_e32 v74, v137, v162
	v_exp_f32_e32 v186, v75
	v_exp_f32_e32 v187, v76
	s_waitcnt lgkmcnt(0)
	v_mfma_f32_32x32x16_bf16 v[82:97], v[138:141], v[114:117], v[82:97]
	v_exp_f32_e32 v188, v77
	v_exp_f32_e32 v189, v78
	v_exp_f32_e32 v199, v79
	v_exp_f32_e32 v200, v80
	v_exp_f32_e32 v201, v81
	v_mfma_f32_32x32x16_bf16 v[82:97], v[142:145], v[110:113], v[82:97]
	v_mfma_f32_32x32x16_bf16 v[82:97], v[66:69], v[106:109], v[82:97]
	ds_read_b128 v[138:141], v158 offset:512
	ds_read_b128 v[66:69], v158 offset:10240
	ds_read_b128 v[142:145], v158 offset:2560
	ds_read_b128 v[146:149], v158 offset:4608
	ds_read_b128 v[150:153], v158 offset:6656
	ds_read_b128 v[154:157], v158 offset:8704
	ds_read_b128 v[158:161], v158 offset:10752
	v_mfma_f32_32x32x16_bf16 v[82:97], v[70:73], v[102:105], v[82:97]
	v_add_f32_e32 v70, v163, v74
	v_add_f32_e32 v70, v164, v70
	s_waitcnt lgkmcnt(0)
	v_mfma_f32_32x32x16_bf16 v[82:97], v[66:69], v[98:101], v[82:97]
	v_add_f32_e32 v66, v165, v70
	v_add_f32_e32 v66, v166, v66
	v_add_f32_e32 v66, v167, v66
	v_add_f32_e32 v66, v168, v66
	v_add_f32_e32 v66, v169, v66
	v_add_f32_e32 v66, v170, v66
	v_add_f32_e32 v202, v171, v66
	v_mfma_f32_32x32x16_bf16 v[66:81], v[138:141], v[118:121], v[34:49]
	v_add_f32_e32 v138, v172, v202
	v_add_f32_e32 v138, v173, v138
	v_add_f32_e32 v138, v174, v138
	v_add_f32_e32 v138, v175, v138
	v_add_f32_e32 v138, v176, v138
	v_add_f32_e32 v138, v177, v138
	v_add_f32_e32 v138, v178, v138
	v_mfma_f32_32x32x16_bf16 v[66:81], v[142:145], v[114:117], v[66:81]
	v_add_f32_e32 v138, v179, v138
	v_add_f32_e32 v138, v180, v138
	v_add_f32_e32 v138, v181, v138
	v_add_f32_e32 v138, v182, v138
	v_add_f32_e32 v138, v183, v138
	v_add_f32_e32 v138, v184, v138
	v_add_f32_e32 v138, v185, v138
	v_mfma_f32_32x32x16_bf16 v[66:81], v[146:149], v[110:113], v[66:81]
	v_add_f32_e32 v138, v186, v138
	v_add_f32_e32 v138, v187, v138
	v_add_f32_e32 v138, v188, v138
	v_add_f32_e32 v138, v189, v138
	v_add_f32_e32 v138, v199, v138
	v_add_f32_e32 v202, v200, v138
	v_cvt_pk_bf16_f32 v138, v137, v162
	v_mfma_f32_32x32x16_bf16 v[66:81], v[150:153], v[106:109], v[66:81]
	v_cvt_pk_bf16_f32 v139, v163, v164
	v_cvt_pk_bf16_f32 v140, v165, v166
	v_cvt_pk_bf16_f32 v141, v167, v168
	v_cvt_pk_bf16_f32 v142, v169, v170
	v_cvt_pk_bf16_f32 v143, v171, v172
	v_cvt_pk_bf16_f32 v144, v173, v174
	s_setprio 1
	v_cvt_pk_bf16_f32 v145, v175, v176
	v_mfma_f32_32x32x16_bf16 v[66:81], v[154:157], v[102:105], v[66:81]
	v_cvt_pk_bf16_f32 v146, v177, v178
	v_cvt_pk_bf16_f32 v147, v179, v180
	v_cvt_pk_bf16_f32 v148, v181, v182
	v_cvt_pk_bf16_f32 v149, v183, v184
	v_cvt_pk_bf16_f32 v150, v185, v186
	v_cvt_pk_bf16_f32 v151, v187, v188
	v_cvt_pk_bf16_f32 v152, v189, v199
	v_mfma_f32_32x32x16_bf16 v[66:81], v[158:161], v[98:101], v[66:81]
	v_cvt_pk_bf16_f32 v153, v200, v201
	v_add_u32_e32 v137, s56, v133
	ds_read_b64_tr_b16 v[154:155], v137 offset:12288
	ds_read_b64_tr_b16 v[156:157], v137 offset:12800
	ds_read_b64_tr_b16 v[158:159], v137 offset:16384
	s_waitcnt lgkmcnt(1)
	v_mfma_f32_32x32x16_bf16 v[18:33], v[154:157], v[138:141], v[18:33]
	ds_read_b64_tr_b16 v[160:161], v137 offset:16896
	ds_read_b64_tr_b16 v[154:155], v137 offset:13312
	s_waitcnt lgkmcnt(1)
	v_mfma_f32_32x32x16_bf16 v[2:17], v[158:161], v[138:141], v[2:17]
	ds_read_b64_tr_b16 v[156:157], v137 offset:13824
	ds_read_b64_tr_b16 v[138:139], v137 offset:17408
	s_waitcnt lgkmcnt(1)
	v_mfma_f32_32x32x16_bf16 v[18:33], v[154:157], v[142:145], v[18:33]
	ds_read_b64_tr_b16 v[140:141], v137 offset:17920
	ds_read_b64_tr_b16 v[154:155], v137 offset:14336
	s_waitcnt lgkmcnt(1)
	v_mfma_f32_32x32x16_bf16 v[2:17], v[138:141], v[142:145], v[2:17]
	ds_read_b64_tr_b16 v[156:157], v137 offset:14848
	ds_read_b64_tr_b16 v[138:139], v137 offset:15360
	ds_read_b64_tr_b16 v[140:141], v137 offset:15872
	ds_read_b64_tr_b16 v[142:143], v137 offset:18432
	ds_read_b64_tr_b16 v[144:145], v137 offset:18944
	ds_read_b64_tr_b16 v[158:159], v137 offset:19456
	ds_read_b64_tr_b16 v[160:161], v137 offset:19968
	v_max_f32_e32 v137, v67, v67
	s_waitcnt lgkmcnt(6)
	v_mfma_f32_32x32x16_bf16 v[18:33], v[154:157], v[146:149], v[18:33]
	v_max_f32_e32 v154, v83, v83
	v_max_f32_e32 v137, v154, v137
	v_max3_f32 v154, v82, v66, v84
	v_max3_f32 v137, v137, v85, v69
	v_max3_f32 v154, v154, v68, v86
	v_max3_f32 v137, v137, v87, v71
	v_max3_f32 v137, v137, v89, v73
	s_waitcnt lgkmcnt(2)
	v_mfma_f32_32x32x16_bf16 v[2:17], v[142:145], v[146:149], v[2:17]
	v_max3_f32 v142, v154, v70, v88
	v_max3_f32 v142, v142, v72, v90
	v_max3_f32 v137, v137, v91, v75
	v_max3_f32 v142, v142, v74, v92
	v_max3_f32 v137, v137, v93, v77
	v_max3_f32 v142, v142, v76, v94
	v_max3_f32 v137, v137, v95, v79
	v_mfma_f32_32x32x16_bf16 v[18:33], v[138:141], v[150:153], v[18:33]
	v_max3_f32 v138, v142, v78, v96
	v_max3_f32 v137, v137, v97, v81
	v_add_f32_e32 v139, v201, v202
	v_max3_f32 v137, v138, v80, v137
	v_add_f32_e32 v136, v136, v139
	v_cmp_lt_f32_e32 vcc, s33, v137
	s_waitcnt lgkmcnt(0)
	v_mfma_f32_32x32x16_bf16 v[2:17], v[158:161], v[150:153], v[2:17]
	s_cbranch_vccz .LBB0_431
	v_mov_b32_e32 v34, v137
	s_nop 1
	v_permlane32_swap_b32 v137, v34
	s_nop 1
	s_nop 0
	v_max3_f32 v36, v137, v34, 0
	v_exp_f32_e64 v38, -v36
	v_add_f32_e32 v135, v135, v36
	v_xor_b32_e32 v34, 0x80000000, v135
	v_pk_add_f32 v[82:83], v[82:83], v[36:37] op_sel_hi:[1,0] neg_lo:[0,1] neg_hi:[0,1]
	v_pk_add_f32 v[84:85], v[84:85], v[36:37] op_sel_hi:[1,0] neg_lo:[0,1] neg_hi:[0,1]
	v_pk_add_f32 v[86:87], v[86:87], v[36:37] op_sel_hi:[1,0] neg_lo:[0,1] neg_hi:[0,1]
	v_pk_add_f32 v[88:89], v[88:89], v[36:37] op_sel_hi:[1,0] neg_lo:[0,1] neg_hi:[0,1]
	v_pk_add_f32 v[90:91], v[90:91], v[36:37] op_sel_hi:[1,0] neg_lo:[0,1] neg_hi:[0,1]
	v_pk_add_f32 v[92:93], v[92:93], v[36:37] op_sel_hi:[1,0] neg_lo:[0,1] neg_hi:[0,1]
	v_pk_add_f32 v[94:95], v[94:95], v[36:37] op_sel_hi:[1,0] neg_lo:[0,1] neg_hi:[0,1]
	v_pk_add_f32 v[96:97], v[96:97], v[36:37] op_sel_hi:[1,0] neg_lo:[0,1] neg_hi:[0,1]
	v_sub_f32_e32 v81, v81, v36
	v_sub_f32_e32 v80, v80, v36
	v_sub_f32_e32 v79, v79, v36
	v_sub_f32_e32 v78, v78, v36
	v_sub_f32_e32 v77, v77, v36
	v_sub_f32_e32 v76, v76, v36
	v_sub_f32_e32 v75, v75, v36
	v_sub_f32_e32 v74, v74, v36
	v_sub_f32_e32 v73, v73, v36
	v_sub_f32_e32 v72, v72, v36
	v_sub_f32_e32 v71, v71, v36
	v_sub_f32_e32 v70, v70, v36
	v_sub_f32_e32 v69, v69, v36
	v_sub_f32_e32 v68, v68, v36
	v_sub_f32_e32 v67, v67, v36
	v_sub_f32_e32 v66, v66, v36
	v_pk_mul_f32 v[32:33], v[32:33], v[38:39] op_sel_hi:[1,0]
	v_pk_mul_f32 v[30:31], v[30:31], v[38:39] op_sel_hi:[1,0]
	v_pk_mul_f32 v[28:29], v[28:29], v[38:39] op_sel_hi:[1,0]
	v_pk_mul_f32 v[26:27], v[26:27], v[38:39] op_sel_hi:[1,0]
	v_pk_mul_f32 v[24:25], v[24:25], v[38:39] op_sel_hi:[1,0]
	v_pk_mul_f32 v[22:23], v[22:23], v[38:39] op_sel_hi:[1,0]
	v_pk_mul_f32 v[20:21], v[20:21], v[38:39] op_sel_hi:[1,0]
	v_pk_mul_f32 v[18:19], v[18:19], v[38:39] op_sel_hi:[1,0]
	v_pk_mul_f32 v[16:17], v[16:17], v[38:39] op_sel_hi:[1,0]
	v_pk_mul_f32 v[14:15], v[14:15], v[38:39] op_sel_hi:[1,0]
	v_pk_mul_f32 v[12:13], v[12:13], v[38:39] op_sel_hi:[1,0]
	v_pk_mul_f32 v[10:11], v[10:11], v[38:39] op_sel_hi:[1,0]
	v_pk_mul_f32 v[8:9], v[8:9], v[38:39] op_sel_hi:[1,0]
	v_pk_mul_f32 v[6:7], v[6:7], v[38:39] op_sel_hi:[1,0]
	v_pk_mul_f32 v[4:5], v[4:5], v[38:39] op_sel_hi:[1,0]
	v_pk_mul_f32 v[2:3], v[2:3], v[38:39] op_sel_hi:[1,0]
	v_mul_f32_e32 v136, v136, v38
	v_mov_b32_e32 v35, v34
	v_mov_b32_e32 v36, v34
	v_mov_b32_e32 v37, v34
	v_mov_b32_e32 v38, v34
	v_mov_b32_e32 v39, v34
	v_mov_b32_e32 v40, v34
	v_mov_b32_e32 v41, v34
	v_mov_b32_e32 v42, v34
	v_mov_b32_e32 v43, v34
	v_mov_b32_e32 v44, v34
	v_mov_b32_e32 v45, v34
	v_mov_b32_e32 v46, v34
	v_mov_b32_e32 v47, v34
	v_mov_b32_e32 v48, v34
	v_mov_b32_e32 v49, v34
	v_mov_b32_e32 v50, v34
	v_mov_b32_e32 v51, v34
	v_mov_b32_e32 v52, v34
	v_mov_b32_e32 v53, v34
	v_mov_b32_e32 v54, v34
	v_mov_b32_e32 v55, v34
	v_mov_b32_e32 v56, v34
	v_mov_b32_e32 v57, v34
	v_mov_b32_e32 v58, v34
	v_mov_b32_e32 v59, v34
	v_mov_b32_e32 v60, v34
	v_mov_b32_e32 v61, v34
	v_mov_b32_e32 v62, v34
	v_mov_b32_e32 v63, v34
	v_mov_b32_e32 v64, v34
	v_mov_b32_e32 v65, v34
